# RW chunk path: token bookkeeping strength-reduced, dead loop-counter setup and fall-through branches removed (as for DN)
# baseline (speedup 1.0000x reference)
.Lrw_tok_ctx:
	s_lshl_b32 s6, s4, 4
	v_readlane_b32 s8, v254, 0
	s_sub_i32 s2, 0xff, s6
	v_readlane_b32 s9, v254, 1
	s_and_b64 s[10:11], s[8:9], exec
	s_cselect_b32 s2, s6, s2
	v_readlane_b32 s3, v254, 3
	s_or_b32 s46, s2, s3
	s_branch .LBB0_857
.Lrw_tok_lat:
	s_lshl_b32 s6, s4, 4
	v_readlane_b32 s8, v254, 0
	s_sub_i32 s2, 0x8ff, s6
	s_add_i32 s3, s6, 0xffffff00
	v_readlane_b32 s9, v254, 1
	s_and_b64 s[10:11], s[8:9], exec
	s_cselect_b32 s2, s3, s2
	v_readlane_b32 s3, v254, 2
	s_add_i32 s46, s2, s3
	s_branch .LBB0_857

.LBB0_853:
	ds_read_b128 v[22:25], v100
	ds_read_b128 v[18:21], v100 offset:16
	ds_read_b128 v[2:5], v100 offset:256
	ds_read_b128 v[6:9], v100 offset:272
	ds_read_b128 v[10:13], v100 offset:512
	ds_read_b128 v[14:17], v100 offset:528
	ds_read_b128 v[34:37], v100 offset:768
	ds_read_b128 v[38:41], v100 offset:784
	ds_read_b128 v[26:29], v100 offset:1024
	ds_read_b128 v[30:33], v100 offset:1040
	ds_read_b32 v94, v101 offset:1280
	ds_read_b64 v[96:97], v1 offset:1536
	s_cmp_lg_u32 s4, 0
	s_cbranch_scc0 .Lrw_tok_ctx
	s_cmp_lg_u32 s4, 16
	s_cbranch_scc0 .Lrw_tok_lat
	v_readlane_b32 s2, v254, 61
	s_lshl_b32 s2, s2, 5
	s_add_i32 s46, s46, s2

.LBB0_859:
	s_nop 0
	v_readfirstlane_b32 s100, v92
	v_readfirstlane_b32 s101, v93
	s_sub_u32 s100, s100, m0
	s_subb_u32 s101, s101, 0
	s_waitcnt lgkmcnt(0)
	v_pk_fma_f32 v[106:107], v[84:85], v[34:35], 0 op_sel_hi:[1,1,0]
	v_pk_fma_f32 v[108:109], v[84:85], v[22:23], 0 op_sel_hi:[1,1,0]
	ds_read_b128 v[70:73], v100 offset:1568
	ds_read_b128 v[66:69], v100 offset:1584
	v_pk_fma_f32 v[106:107], v[86:87], v[36:37], v[106:107]
	v_pk_fma_f32 v[108:109], v[86:87], v[24:25], v[108:109]
	ds_read_b128 v[50:53], v100 offset:1824
	ds_read_b128 v[46:49], v100 offset:1840
	v_pk_fma_f32 v[106:107], v[88:89], v[38:39], v[106:107]
	v_pk_fma_f32 v[108:109], v[88:89], v[18:19], v[108:109]
	ds_read_b128 v[54:57], v100 offset:2080
	ds_read_b128 v[42:45], v100 offset:2096
	v_pk_fma_f32 v[106:107], v[90:91], v[40:41], v[106:107]
	v_pk_fma_f32 v[108:109], v[90:91], v[20:21], v[108:109]
	ds_read_b128 v[78:81], v100 offset:2336
	ds_read_b128 v[74:77], v100 offset:2352
	v_add_f32_e32 v130, v106, v107
	v_add_f32_e32 v131, v108, v109
	v_pk_mul_f32 v[114:115], v[84:85], v[2:3]
	v_add_f32_dpp v130, v130, v130 quad_perm:[1,0,3,2] row_mask:0xf bank_mask:0xf bound_ctrl:1
	v_add_f32_dpp v131, v131, v131 quad_perm:[1,0,3,2] row_mask:0xf bank_mask:0xf bound_ctrl:1
	v_pk_mul_f32 v[116:117], v[86:87], v[4:5]
	v_add_f32_dpp v130, v130, v130 quad_perm:[2,3,0,1] row_mask:0xf bank_mask:0xf bound_ctrl:1
	v_add_f32_dpp v131, v131, v131 quad_perm:[2,3,0,1] row_mask:0xf bank_mask:0xf bound_ctrl:1
	v_pk_mul_f32 v[118:119], v[88:89], v[6:7]
	v_add_f32_dpp v130, v130, v130 row_half_mirror row_mask:0xf bank_mask:0xf bound_ctrl:1
	v_add_f32_dpp v131, v131, v131 row_half_mirror row_mask:0xf bank_mask:0xf bound_ctrl:1
	v_pk_mul_f32 v[120:121], v[90:91], v[8:9]
	ds_read_b128 v[62:65], v100 offset:2592
	ds_read_b128 v[58:61], v100 offset:2608
	v_mul_f32_e32 v132, v130, v96
	v_mul_f32_e32 v133, v97, v94
	ds_read_b32 v0, v101 offset:2848
	v_add_f32_e32 v131, v132, v131
	ds_read_b64 v[98:99], v1 offset:3104
	v_add_f32_e32 v131, v133, v131
	v_pk_fma_f32 v[114:115], v[130:131], v[26:27], v[114:115] op_sel_hi:[0,1,1]
	v_pk_fma_f32 v[116:117], v[130:131], v[28:29], v[116:117] op_sel_hi:[0,1,1]
	v_cvt_pk_bf16_f32 v132, v131, v131
	v_pk_fma_f32 v[84:85], v[94:95], v[10:11], v[114:115] op_sel_hi:[0,1,1]
	global_store_short v144, v132, s[100:101]
	v_pk_fma_f32 v[118:119], v[130:131], v[30:31], v[118:119] op_sel_hi:[0,1,1]
	v_pk_fma_f32 v[86:87], v[94:95], v[12:13], v[116:117] op_sel_hi:[0,1,1]
	v_pk_fma_f32 v[120:121], v[130:131], v[32:33], v[120:121] op_sel_hi:[0,1,1]
	v_pk_fma_f32 v[88:89], v[94:95], v[14:15], v[118:119] op_sel_hi:[0,1,1]
	v_pk_fma_f32 v[90:91], v[94:95], v[16:17], v[120:121] op_sel_hi:[0,1,1]
	s_waitcnt lgkmcnt(0)
	v_pk_fma_f32 v[110:111], v[84:85], v[78:79], 0 op_sel_hi:[1,1,0]
	v_pk_fma_f32 v[112:113], v[84:85], v[70:71], 0 op_sel_hi:[1,1,0]
	ds_read_b128 v[22:25], v100 offset:3136
	ds_read_b128 v[18:21], v100 offset:3152
	v_pk_fma_f32 v[110:111], v[86:87], v[80:81], v[110:111]
	v_pk_fma_f32 v[112:113], v[86:87], v[72:73], v[112:113]
	ds_read_b128 v[2:5], v100 offset:3392
	ds_read_b128 v[6:9], v100 offset:3408
	v_pk_fma_f32 v[110:111], v[88:89], v[74:75], v[110:111]
	v_pk_fma_f32 v[112:113], v[88:89], v[66:67], v[112:113]
	ds_read_b128 v[10:13], v100 offset:3648
	ds_read_b128 v[14:17], v100 offset:3664
	v_pk_fma_f32 v[110:111], v[90:91], v[76:77], v[110:111]
	v_pk_fma_f32 v[112:113], v[90:91], v[68:69], v[112:113]
	ds_read_b128 v[34:37], v100 offset:3904
	ds_read_b128 v[38:41], v100 offset:3920
	v_add_f32_e32 v140, v110, v111
	v_add_f32_e32 v141, v112, v113
	v_pk_mul_f32 v[114:115], v[84:85], v[50:51]
	v_add_f32_dpp v140, v140, v140 quad_perm:[1,0,3,2] row_mask:0xf bank_mask:0xf bound_ctrl:1
	v_add_f32_dpp v141, v141, v141 quad_perm:[1,0,3,2] row_mask:0xf bank_mask:0xf bound_ctrl:1
	v_pk_mul_f32 v[116:117], v[86:87], v[52:53]
	v_add_f32_dpp v140, v140, v140 quad_perm:[2,3,0,1] row_mask:0xf bank_mask:0xf bound_ctrl:1
	v_add_f32_dpp v141, v141, v141 quad_perm:[2,3,0,1] row_mask:0xf bank_mask:0xf bound_ctrl:1
	v_pk_mul_f32 v[118:119], v[88:89], v[46:47]
	v_add_f32_dpp v140, v140, v140 row_half_mirror row_mask:0xf bank_mask:0xf bound_ctrl:1
	v_add_f32_dpp v141, v141, v141 row_half_mirror row_mask:0xf bank_mask:0xf bound_ctrl:1
	v_pk_mul_f32 v[120:121], v[90:91], v[48:49]
	ds_read_b128 v[26:29], v100 offset:4160
	ds_read_b128 v[30:33], v100 offset:4176
	v_mul_f32_e32 v142, v140, v98
	v_mul_f32_e32 v143, v99, v0
	ds_read_b32 v94, v101 offset:4416
	v_add_f32_e32 v141, v142, v141
	ds_read_b64 v[96:97], v1 offset:4672
	v_add_f32_e32 v141, v143, v141
	v_pk_fma_f32 v[114:115], v[140:141], v[62:63], v[114:115] op_sel_hi:[0,1,1]
	v_pk_fma_f32 v[116:117], v[140:141], v[64:65], v[116:117] op_sel_hi:[0,1,1]
	v_cvt_pk_bf16_f32 v142, v141, v141
	v_pk_fma_f32 v[84:85], v[0:1], v[54:55], v[114:115] op_sel_hi:[0,1,1]
	global_store_short v145, v142, s[100:101]
	v_pk_fma_f32 v[118:119], v[140:141], v[58:59], v[118:119] op_sel_hi:[0,1,1]
	v_pk_fma_f32 v[86:87], v[0:1], v[56:57], v[116:117] op_sel_hi:[0,1,1]
	v_pk_fma_f32 v[120:121], v[140:141], v[60:61], v[120:121] op_sel_hi:[0,1,1]
	v_pk_fma_f32 v[88:89], v[0:1], v[42:43], v[118:119] op_sel_hi:[0,1,1]
	v_pk_fma_f32 v[90:91], v[0:1], v[44:45], v[120:121] op_sel_hi:[0,1,1]
	s_waitcnt lgkmcnt(0)
	v_pk_fma_f32 v[106:107], v[84:85], v[34:35], 0 op_sel_hi:[1,1,0]
	v_pk_fma_f32 v[108:109], v[84:85], v[22:23], 0 op_sel_hi:[1,1,0]
	ds_read_b128 v[70:73], v100 offset:4704
	ds_read_b128 v[66:69], v100 offset:4720
	v_pk_fma_f32 v[106:107], v[86:87], v[36:37], v[106:107]
	v_pk_fma_f32 v[108:109], v[86:87], v[24:25], v[108:109]
	ds_read_b128 v[50:53], v100 offset:4960
	ds_read_b128 v[46:49], v100 offset:4976
	v_pk_fma_f32 v[106:107], v[88:89], v[38:39], v[106:107]
	v_pk_fma_f32 v[108:109], v[88:89], v[18:19], v[108:109]
	ds_read_b128 v[54:57], v100 offset:5216
	ds_read_b128 v[42:45], v100 offset:5232
	v_pk_fma_f32 v[106:107], v[90:91], v[40:41], v[106:107]
	v_pk_fma_f32 v[108:109], v[90:91], v[20:21], v[108:109]
	ds_read_b128 v[78:81], v100 offset:5472
	ds_read_b128 v[74:77], v100 offset:5488
	v_add_f32_e32 v130, v106, v107
	v_add_f32_e32 v131, v108, v109
	v_pk_mul_f32 v[114:115], v[84:85], v[2:3]
	v_add_f32_dpp v130, v130, v130 quad_perm:[1,0,3,2] row_mask:0xf bank_mask:0xf bound_ctrl:1
	v_add_f32_dpp v131, v131, v131 quad_perm:[1,0,3,2] row_mask:0xf bank_mask:0xf bound_ctrl:1
	v_pk_mul_f32 v[116:117], v[86:87], v[4:5]
	v_add_f32_dpp v130, v130, v130 quad_perm:[2,3,0,1] row_mask:0xf bank_mask:0xf bound_ctrl:1
	v_add_f32_dpp v131, v131, v131 quad_perm:[2,3,0,1] row_mask:0xf bank_mask:0xf bound_ctrl:1
	v_pk_mul_f32 v[118:119], v[88:89], v[6:7]
	v_add_f32_dpp v130, v130, v130 row_half_mirror row_mask:0xf bank_mask:0xf bound_ctrl:1
	v_add_f32_dpp v131, v131, v131 row_half_mirror row_mask:0xf bank_mask:0xf bound_ctrl:1
	v_pk_mul_f32 v[120:121], v[90:91], v[8:9]
	ds_read_b128 v[62:65], v100 offset:5728
	ds_read_b128 v[58:61], v100 offset:5744
	v_mul_f32_e32 v132, v130, v96
	v_mul_f32_e32 v133, v97, v94
	ds_read_b32 v0, v101 offset:5984
	v_add_f32_e32 v131, v132, v131
	ds_read_b64 v[98:99], v1 offset:6240
	v_add_f32_e32 v131, v133, v131
	v_pk_fma_f32 v[114:115], v[130:131], v[26:27], v[114:115] op_sel_hi:[0,1,1]
	v_pk_fma_f32 v[116:117], v[130:131], v[28:29], v[116:117] op_sel_hi:[0,1,1]
	v_cvt_pk_bf16_f32 v132, v131, v131
	v_pk_fma_f32 v[84:85], v[94:95], v[10:11], v[114:115] op_sel_hi:[0,1,1]
	global_store_short v146, v132, s[100:101]
	v_pk_fma_f32 v[118:119], v[130:131], v[30:31], v[118:119] op_sel_hi:[0,1,1]
	v_pk_fma_f32 v[86:87], v[94:95], v[12:13], v[116:117] op_sel_hi:[0,1,1]
	v_pk_fma_f32 v[120:121], v[130:131], v[32:33], v[120:121] op_sel_hi:[0,1,1]
	v_pk_fma_f32 v[88:89], v[94:95], v[14:15], v[118:119] op_sel_hi:[0,1,1]
	v_pk_fma_f32 v[90:91], v[94:95], v[16:17], v[120:121] op_sel_hi:[0,1,1]
	s_waitcnt lgkmcnt(0)
	v_pk_fma_f32 v[110:111], v[84:85], v[78:79], 0 op_sel_hi:[1,1,0]
	v_pk_fma_f32 v[112:113], v[84:85], v[70:71], 0 op_sel_hi:[1,1,0]
	ds_read_b128 v[22:25], v100 offset:6272
	ds_read_b128 v[18:21], v100 offset:6288
	v_pk_fma_f32 v[110:111], v[86:87], v[80:81], v[110:111]
	v_pk_fma_f32 v[112:113], v[86:87], v[72:73], v[112:113]
	ds_read_b128 v[2:5], v100 offset:6528
	ds_read_b128 v[6:9], v100 offset:6544
	v_pk_fma_f32 v[110:111], v[88:89], v[74:75], v[110:111]
	v_pk_fma_f32 v[112:113], v[88:89], v[66:67], v[112:113]
	ds_read_b128 v[10:13], v100 offset:6784
	ds_read_b128 v[14:17], v100 offset:6800
	v_pk_fma_f32 v[110:111], v[90:91], v[76:77], v[110:111]
	v_pk_fma_f32 v[112:113], v[90:91], v[68:69], v[112:113]
	ds_read_b128 v[34:37], v100 offset:7040
	ds_read_b128 v[38:41], v100 offset:7056
	v_add_f32_e32 v140, v110, v111
	v_add_f32_e32 v141, v112, v113
	v_pk_mul_f32 v[114:115], v[84:85], v[50:51]
	v_add_f32_dpp v140, v140, v140 quad_perm:[1,0,3,2] row_mask:0xf bank_mask:0xf bound_ctrl:1
	v_add_f32_dpp v141, v141, v141 quad_perm:[1,0,3,2] row_mask:0xf bank_mask:0xf bound_ctrl:1
	v_pk_mul_f32 v[116:117], v[86:87], v[52:53]
	v_add_f32_dpp v140, v140, v140 quad_perm:[2,3,0,1] row_mask:0xf bank_mask:0xf bound_ctrl:1
	v_add_f32_dpp v141, v141, v141 quad_perm:[2,3,0,1] row_mask:0xf bank_mask:0xf bound_ctrl:1
	v_pk_mul_f32 v[118:119], v[88:89], v[46:47]
	v_add_f32_dpp v140, v140, v140 row_half_mirror row_mask:0xf bank_mask:0xf bound_ctrl:1
	v_add_f32_dpp v141, v141, v141 row_half_mirror row_mask:0xf bank_mask:0xf bound_ctrl:1
	v_pk_mul_f32 v[120:121], v[90:91], v[48:49]
	ds_read_b128 v[26:29], v100 offset:7296
	ds_read_b128 v[30:33], v100 offset:7312
	v_mul_f32_e32 v142, v140, v98
	v_mul_f32_e32 v143, v99, v0
	ds_read_b32 v94, v101 offset:7552
	v_add_f32_e32 v141, v142, v141
	ds_read_b64 v[96:97], v1 offset:7808
	v_add_f32_e32 v141, v143, v141
	v_pk_fma_f32 v[114:115], v[140:141], v[62:63], v[114:115] op_sel_hi:[0,1,1]
	v_pk_fma_f32 v[116:117], v[140:141], v[64:65], v[116:117] op_sel_hi:[0,1,1]
	v_cvt_pk_bf16_f32 v142, v141, v141
	v_pk_fma_f32 v[84:85], v[0:1], v[54:55], v[114:115] op_sel_hi:[0,1,1]
	global_store_short v147, v142, s[100:101]
	v_pk_fma_f32 v[118:119], v[140:141], v[58:59], v[118:119] op_sel_hi:[0,1,1]
	v_pk_fma_f32 v[86:87], v[0:1], v[56:57], v[116:117] op_sel_hi:[0,1,1]
	v_pk_fma_f32 v[120:121], v[140:141], v[60:61], v[120:121] op_sel_hi:[0,1,1]
	v_pk_fma_f32 v[88:89], v[0:1], v[42:43], v[118:119] op_sel_hi:[0,1,1]
	v_pk_fma_f32 v[90:91], v[0:1], v[44:45], v[120:121] op_sel_hi:[0,1,1]
	s_waitcnt lgkmcnt(0)
	v_pk_fma_f32 v[106:107], v[84:85], v[34:35], 0 op_sel_hi:[1,1,0]
	v_pk_fma_f32 v[108:109], v[84:85], v[22:23], 0 op_sel_hi:[1,1,0]
	ds_read_b128 v[70:73], v100 offset:7840
	ds_read_b128 v[66:69], v100 offset:7856
	v_pk_fma_f32 v[106:107], v[86:87], v[36:37], v[106:107]
	v_pk_fma_f32 v[108:109], v[86:87], v[24:25], v[108:109]
	ds_read_b128 v[50:53], v100 offset:8096
	ds_read_b128 v[46:49], v100 offset:8112
	v_pk_fma_f32 v[106:107], v[88:89], v[38:39], v[106:107]
	v_pk_fma_f32 v[108:109], v[88:89], v[18:19], v[108:109]
	ds_read_b128 v[54:57], v100 offset:8352
	ds_read_b128 v[42:45], v100 offset:8368
	v_pk_fma_f32 v[106:107], v[90:91], v[40:41], v[106:107]
	v_pk_fma_f32 v[108:109], v[90:91], v[20:21], v[108:109]
	ds_read_b128 v[78:81], v100 offset:8608
	ds_read_b128 v[74:77], v100 offset:8624
	v_add_f32_e32 v130, v106, v107
	v_add_f32_e32 v131, v108, v109
	v_pk_mul_f32 v[114:115], v[84:85], v[2:3]
	v_add_f32_dpp v130, v130, v130 quad_perm:[1,0,3,2] row_mask:0xf bank_mask:0xf bound_ctrl:1
	v_add_f32_dpp v131, v131, v131 quad_perm:[1,0,3,2] row_mask:0xf bank_mask:0xf bound_ctrl:1
	v_pk_mul_f32 v[116:117], v[86:87], v[4:5]
	v_add_f32_dpp v130, v130, v130 quad_perm:[2,3,0,1] row_mask:0xf bank_mask:0xf bound_ctrl:1
	v_add_f32_dpp v131, v131, v131 quad_perm:[2,3,0,1] row_mask:0xf bank_mask:0xf bound_ctrl:1
	v_pk_mul_f32 v[118:119], v[88:89], v[6:7]
	v_add_f32_dpp v130, v130, v130 row_half_mirror row_mask:0xf bank_mask:0xf bound_ctrl:1
	v_add_f32_dpp v131, v131, v131 row_half_mirror row_mask:0xf bank_mask:0xf bound_ctrl:1
	v_pk_mul_f32 v[120:121], v[90:91], v[8:9]
	ds_read_b128 v[62:65], v100 offset:8864
	ds_read_b128 v[58:61], v100 offset:8880
	v_mul_f32_e32 v132, v130, v96
	v_mul_f32_e32 v133, v97, v94
	ds_read_b32 v0, v101 offset:9120
	v_add_f32_e32 v131, v132, v131
	ds_read_b64 v[98:99], v1 offset:9376
	v_add_f32_e32 v131, v133, v131
	v_pk_fma_f32 v[114:115], v[130:131], v[26:27], v[114:115] op_sel_hi:[0,1,1]
	v_pk_fma_f32 v[116:117], v[130:131], v[28:29], v[116:117] op_sel_hi:[0,1,1]
	v_cvt_pk_bf16_f32 v132, v131, v131
	v_pk_fma_f32 v[84:85], v[94:95], v[10:11], v[114:115] op_sel_hi:[0,1,1]
	global_store_short v148, v132, s[100:101]
	v_pk_fma_f32 v[118:119], v[130:131], v[30:31], v[118:119] op_sel_hi:[0,1,1]
	v_pk_fma_f32 v[86:87], v[94:95], v[12:13], v[116:117] op_sel_hi:[0,1,1]
	v_pk_fma_f32 v[120:121], v[130:131], v[32:33], v[120:121] op_sel_hi:[0,1,1]
	v_pk_fma_f32 v[88:89], v[94:95], v[14:15], v[118:119] op_sel_hi:[0,1,1]
	v_pk_fma_f32 v[90:91], v[94:95], v[16:17], v[120:121] op_sel_hi:[0,1,1]
	s_waitcnt lgkmcnt(0)
	v_pk_fma_f32 v[110:111], v[84:85], v[78:79], 0 op_sel_hi:[1,1,0]
	v_pk_fma_f32 v[112:113], v[84:85], v[70:71], 0 op_sel_hi:[1,1,0]
	ds_read_b128 v[22:25], v100 offset:9408
	ds_read_b128 v[18:21], v100 offset:9424
	v_pk_fma_f32 v[110:111], v[86:87], v[80:81], v[110:111]
	v_pk_fma_f32 v[112:113], v[86:87], v[72:73], v[112:113]
	ds_read_b128 v[2:5], v100 offset:9664
	ds_read_b128 v[6:9], v100 offset:9680
	v_pk_fma_f32 v[110:111], v[88:89], v[74:75], v[110:111]
	v_pk_fma_f32 v[112:113], v[88:89], v[66:67], v[112:113]
	ds_read_b128 v[10:13], v100 offset:9920
	ds_read_b128 v[14:17], v100 offset:9936
	v_pk_fma_f32 v[110:111], v[90:91], v[76:77], v[110:111]
	v_pk_fma_f32 v[112:113], v[90:91], v[68:69], v[112:113]
	ds_read_b128 v[34:37], v100 offset:10176
	ds_read_b128 v[38:41], v100 offset:10192
	v_add_f32_e32 v140, v110, v111
	v_add_f32_e32 v141, v112, v113
	v_pk_mul_f32 v[114:115], v[84:85], v[50:51]
	v_add_f32_dpp v140, v140, v140 quad_perm:[1,0,3,2] row_mask:0xf bank_mask:0xf bound_ctrl:1
	v_add_f32_dpp v141, v141, v141 quad_perm:[1,0,3,2] row_mask:0xf bank_mask:0xf bound_ctrl:1
	v_pk_mul_f32 v[116:117], v[86:87], v[52:53]
	v_add_f32_dpp v140, v140, v140 quad_perm:[2,3,0,1] row_mask:0xf bank_mask:0xf bound_ctrl:1
	v_add_f32_dpp v141, v141, v141 quad_perm:[2,3,0,1] row_mask:0xf bank_mask:0xf bound_ctrl:1
	v_pk_mul_f32 v[118:119], v[88:89], v[46:47]
	v_add_f32_dpp v140, v140, v140 row_half_mirror row_mask:0xf bank_mask:0xf bound_ctrl:1
	v_add_f32_dpp v141, v141, v141 row_half_mirror row_mask:0xf bank_mask:0xf bound_ctrl:1
	v_pk_mul_f32 v[120:121], v[90:91], v[48:49]
	ds_read_b128 v[26:29], v100 offset:10432
	ds_read_b128 v[30:33], v100 offset:10448
	v_mul_f32_e32 v142, v140, v98
	v_mul_f32_e32 v143, v99, v0
	ds_read_b32 v94, v101 offset:10688
	v_add_f32_e32 v141, v142, v141
	ds_read_b64 v[96:97], v1 offset:10944
	v_add_f32_e32 v141, v143, v141
	v_pk_fma_f32 v[114:115], v[140:141], v[62:63], v[114:115] op_sel_hi:[0,1,1]
	v_pk_fma_f32 v[116:117], v[140:141], v[64:65], v[116:117] op_sel_hi:[0,1,1]
	v_cvt_pk_bf16_f32 v142, v141, v141
	v_pk_fma_f32 v[84:85], v[0:1], v[54:55], v[114:115] op_sel_hi:[0,1,1]
	global_store_short v149, v142, s[100:101]
	v_pk_fma_f32 v[118:119], v[140:141], v[58:59], v[118:119] op_sel_hi:[0,1,1]
	v_pk_fma_f32 v[86:87], v[0:1], v[56:57], v[116:117] op_sel_hi:[0,1,1]
	v_pk_fma_f32 v[120:121], v[140:141], v[60:61], v[120:121] op_sel_hi:[0,1,1]
	v_pk_fma_f32 v[88:89], v[0:1], v[42:43], v[118:119] op_sel_hi:[0,1,1]
	v_pk_fma_f32 v[90:91], v[0:1], v[44:45], v[120:121] op_sel_hi:[0,1,1]
	s_waitcnt lgkmcnt(0)
	v_pk_fma_f32 v[106:107], v[84:85], v[34:35], 0 op_sel_hi:[1,1,0]
	v_pk_fma_f32 v[108:109], v[84:85], v[22:23], 0 op_sel_hi:[1,1,0]
	ds_read_b128 v[70:73], v100 offset:10976
	ds_read_b128 v[66:69], v100 offset:10992
	v_pk_fma_f32 v[106:107], v[86:87], v[36:37], v[106:107]
	v_pk_fma_f32 v[108:109], v[86:87], v[24:25], v[108:109]
	ds_read_b128 v[50:53], v100 offset:11232
	ds_read_b128 v[46:49], v100 offset:11248
	v_pk_fma_f32 v[106:107], v[88:89], v[38:39], v[106:107]
	v_pk_fma_f32 v[108:109], v[88:89], v[18:19], v[108:109]
	ds_read_b128 v[54:57], v100 offset:11488
	ds_read_b128 v[42:45], v100 offset:11504
	v_pk_fma_f32 v[106:107], v[90:91], v[40:41], v[106:107]
	v_pk_fma_f32 v[108:109], v[90:91], v[20:21], v[108:109]
	ds_read_b128 v[78:81], v100 offset:11744
	ds_read_b128 v[74:77], v100 offset:11760
	v_add_f32_e32 v130, v106, v107
	v_add_f32_e32 v131, v108, v109
	v_pk_mul_f32 v[114:115], v[84:85], v[2:3]
	v_add_f32_dpp v130, v130, v130 quad_perm:[1,0,3,2] row_mask:0xf bank_mask:0xf bound_ctrl:1
	v_add_f32_dpp v131, v131, v131 quad_perm:[1,0,3,2] row_mask:0xf bank_mask:0xf bound_ctrl:1
	v_pk_mul_f32 v[116:117], v[86:87], v[4:5]
	v_add_f32_dpp v130, v130, v130 quad_perm:[2,3,0,1] row_mask:0xf bank_mask:0xf bound_ctrl:1
	v_add_f32_dpp v131, v131, v131 quad_perm:[2,3,0,1] row_mask:0xf bank_mask:0xf bound_ctrl:1
	v_pk_mul_f32 v[118:119], v[88:89], v[6:7]
	v_add_f32_dpp v130, v130, v130 row_half_mirror row_mask:0xf bank_mask:0xf bound_ctrl:1
	v_add_f32_dpp v131, v131, v131 row_half_mirror row_mask:0xf bank_mask:0xf bound_ctrl:1
	v_pk_mul_f32 v[120:121], v[90:91], v[8:9]
	ds_read_b128 v[62:65], v100 offset:12000
	ds_read_b128 v[58:61], v100 offset:12016
	v_mul_f32_e32 v132, v130, v96
	v_mul_f32_e32 v133, v97, v94
	ds_read_b32 v0, v101 offset:12256
	v_add_f32_e32 v131, v132, v131
	ds_read_b64 v[98:99], v1 offset:12512
	v_add_f32_e32 v131, v133, v131
	v_pk_fma_f32 v[114:115], v[130:131], v[26:27], v[114:115] op_sel_hi:[0,1,1]
	v_pk_fma_f32 v[116:117], v[130:131], v[28:29], v[116:117] op_sel_hi:[0,1,1]
	v_cvt_pk_bf16_f32 v132, v131, v131
	v_pk_fma_f32 v[84:85], v[94:95], v[10:11], v[114:115] op_sel_hi:[0,1,1]
	global_store_short v150, v132, s[100:101]
	v_pk_fma_f32 v[118:119], v[130:131], v[30:31], v[118:119] op_sel_hi:[0,1,1]
	v_pk_fma_f32 v[86:87], v[94:95], v[12:13], v[116:117] op_sel_hi:[0,1,1]
	v_pk_fma_f32 v[120:121], v[130:131], v[32:33], v[120:121] op_sel_hi:[0,1,1]
	v_pk_fma_f32 v[88:89], v[94:95], v[14:15], v[118:119] op_sel_hi:[0,1,1]
	v_pk_fma_f32 v[90:91], v[94:95], v[16:17], v[120:121] op_sel_hi:[0,1,1]
	s_waitcnt lgkmcnt(0)
	v_pk_fma_f32 v[110:111], v[84:85], v[78:79], 0 op_sel_hi:[1,1,0]
	v_pk_fma_f32 v[112:113], v[84:85], v[70:71], 0 op_sel_hi:[1,1,0]
	ds_read_b128 v[22:25], v100 offset:12544
	ds_read_b128 v[18:21], v100 offset:12560
	v_pk_fma_f32 v[110:111], v[86:87], v[80:81], v[110:111]
	v_pk_fma_f32 v[112:113], v[86:87], v[72:73], v[112:113]
	ds_read_b128 v[2:5], v100 offset:12800
	ds_read_b128 v[6:9], v100 offset:12816
	v_pk_fma_f32 v[110:111], v[88:89], v[74:75], v[110:111]
	v_pk_fma_f32 v[112:113], v[88:89], v[66:67], v[112:113]
	ds_read_b128 v[10:13], v100 offset:13056
	ds_read_b128 v[14:17], v100 offset:13072
	v_pk_fma_f32 v[110:111], v[90:91], v[76:77], v[110:111]
	v_pk_fma_f32 v[112:113], v[90:91], v[68:69], v[112:113]
	ds_read_b128 v[34:37], v100 offset:13312
	ds_read_b128 v[38:41], v100 offset:13328
	v_add_f32_e32 v140, v110, v111
	v_add_f32_e32 v141, v112, v113
	v_pk_mul_f32 v[114:115], v[84:85], v[50:51]
	v_add_f32_dpp v140, v140, v140 quad_perm:[1,0,3,2] row_mask:0xf bank_mask:0xf bound_ctrl:1
	v_add_f32_dpp v141, v141, v141 quad_perm:[1,0,3,2] row_mask:0xf bank_mask:0xf bound_ctrl:1
	v_pk_mul_f32 v[116:117], v[86:87], v[52:53]
	v_add_f32_dpp v140, v140, v140 quad_perm:[2,3,0,1] row_mask:0xf bank_mask:0xf bound_ctrl:1
	v_add_f32_dpp v141, v141, v141 quad_perm:[2,3,0,1] row_mask:0xf bank_mask:0xf bound_ctrl:1
	v_pk_mul_f32 v[118:119], v[88:89], v[46:47]
	v_add_f32_dpp v140, v140, v140 row_half_mirror row_mask:0xf bank_mask:0xf bound_ctrl:1
	v_add_f32_dpp v141, v141, v141 row_half_mirror row_mask:0xf bank_mask:0xf bound_ctrl:1
	v_pk_mul_f32 v[120:121], v[90:91], v[48:49]
	ds_read_b128 v[26:29], v100 offset:13568
	ds_read_b128 v[30:33], v100 offset:13584
	v_mul_f32_e32 v142, v140, v98
	v_mul_f32_e32 v143, v99, v0
	ds_read_b32 v94, v101 offset:13824
	v_add_f32_e32 v141, v142, v141
	ds_read_b64 v[96:97], v1 offset:14080
	v_add_f32_e32 v141, v143, v141
	v_pk_fma_f32 v[114:115], v[140:141], v[62:63], v[114:115] op_sel_hi:[0,1,1]
	v_pk_fma_f32 v[116:117], v[140:141], v[64:65], v[116:117] op_sel_hi:[0,1,1]
	v_cvt_pk_bf16_f32 v142, v141, v141
	v_pk_fma_f32 v[84:85], v[0:1], v[54:55], v[114:115] op_sel_hi:[0,1,1]
	global_store_short v151, v142, s[100:101]
	v_pk_fma_f32 v[118:119], v[140:141], v[58:59], v[118:119] op_sel_hi:[0,1,1]
	v_pk_fma_f32 v[86:87], v[0:1], v[56:57], v[116:117] op_sel_hi:[0,1,1]
	v_pk_fma_f32 v[120:121], v[140:141], v[60:61], v[120:121] op_sel_hi:[0,1,1]
	v_pk_fma_f32 v[88:89], v[0:1], v[42:43], v[118:119] op_sel_hi:[0,1,1]
	v_pk_fma_f32 v[90:91], v[0:1], v[44:45], v[120:121] op_sel_hi:[0,1,1]
	s_waitcnt lgkmcnt(0)
	v_pk_fma_f32 v[106:107], v[84:85], v[34:35], 0 op_sel_hi:[1,1,0]
	v_pk_fma_f32 v[108:109], v[84:85], v[22:23], 0 op_sel_hi:[1,1,0]
	ds_read_b128 v[70:73], v100 offset:14112
	ds_read_b128 v[66:69], v100 offset:14128
	v_pk_fma_f32 v[106:107], v[86:87], v[36:37], v[106:107]
	v_pk_fma_f32 v[108:109], v[86:87], v[24:25], v[108:109]
	ds_read_b128 v[50:53], v100 offset:14368
	ds_read_b128 v[46:49], v100 offset:14384
	v_pk_fma_f32 v[106:107], v[88:89], v[38:39], v[106:107]
	v_pk_fma_f32 v[108:109], v[88:89], v[18:19], v[108:109]
	ds_read_b128 v[54:57], v100 offset:14624
	ds_read_b128 v[42:45], v100 offset:14640
	v_pk_fma_f32 v[106:107], v[90:91], v[40:41], v[106:107]
	v_pk_fma_f32 v[108:109], v[90:91], v[20:21], v[108:109]
	ds_read_b128 v[78:81], v100 offset:14880
	ds_read_b128 v[74:77], v100 offset:14896
	v_add_f32_e32 v130, v106, v107
	v_add_f32_e32 v131, v108, v109
	v_pk_mul_f32 v[114:115], v[84:85], v[2:3]
	v_add_f32_dpp v130, v130, v130 quad_perm:[1,0,3,2] row_mask:0xf bank_mask:0xf bound_ctrl:1
	v_add_f32_dpp v131, v131, v131 quad_perm:[1,0,3,2] row_mask:0xf bank_mask:0xf bound_ctrl:1
	v_pk_mul_f32 v[116:117], v[86:87], v[4:5]
	v_add_f32_dpp v130, v130, v130 quad_perm:[2,3,0,1] row_mask:0xf bank_mask:0xf bound_ctrl:1
	v_add_f32_dpp v131, v131, v131 quad_perm:[2,3,0,1] row_mask:0xf bank_mask:0xf bound_ctrl:1
	v_pk_mul_f32 v[118:119], v[88:89], v[6:7]
	v_add_f32_dpp v130, v130, v130 row_half_mirror row_mask:0xf bank_mask:0xf bound_ctrl:1
	v_add_f32_dpp v131, v131, v131 row_half_mirror row_mask:0xf bank_mask:0xf bound_ctrl:1
	v_pk_mul_f32 v[120:121], v[90:91], v[8:9]
	ds_read_b128 v[62:65], v100 offset:15136
	ds_read_b128 v[58:61], v100 offset:15152
	v_mul_f32_e32 v132, v130, v96
	v_mul_f32_e32 v133, v97, v94
	ds_read_b32 v0, v101 offset:15392
	v_add_f32_e32 v131, v132, v131
	ds_read_b64 v[98:99], v1 offset:15648
	v_add_f32_e32 v131, v133, v131
	v_pk_fma_f32 v[114:115], v[130:131], v[26:27], v[114:115] op_sel_hi:[0,1,1]
	v_pk_fma_f32 v[116:117], v[130:131], v[28:29], v[116:117] op_sel_hi:[0,1,1]
	v_cvt_pk_bf16_f32 v132, v131, v131
	v_pk_fma_f32 v[84:85], v[94:95], v[10:11], v[114:115] op_sel_hi:[0,1,1]
	global_store_short v152, v132, s[100:101]
	v_pk_fma_f32 v[118:119], v[130:131], v[30:31], v[118:119] op_sel_hi:[0,1,1]
	v_pk_fma_f32 v[86:87], v[94:95], v[12:13], v[116:117] op_sel_hi:[0,1,1]
	v_pk_fma_f32 v[120:121], v[130:131], v[32:33], v[120:121] op_sel_hi:[0,1,1]
	v_pk_fma_f32 v[88:89], v[94:95], v[14:15], v[118:119] op_sel_hi:[0,1,1]
	v_pk_fma_f32 v[90:91], v[94:95], v[16:17], v[120:121] op_sel_hi:[0,1,1]
	s_waitcnt lgkmcnt(0)
	v_pk_fma_f32 v[110:111], v[84:85], v[78:79], 0 op_sel_hi:[1,1,0]
	v_pk_fma_f32 v[112:113], v[84:85], v[70:71], 0 op_sel_hi:[1,1,0]
	ds_read_b128 v[22:25], v100 offset:15680
	ds_read_b128 v[18:21], v100 offset:15696
	v_pk_fma_f32 v[110:111], v[86:87], v[80:81], v[110:111]
	v_pk_fma_f32 v[112:113], v[86:87], v[72:73], v[112:113]
	ds_read_b128 v[2:5], v100 offset:15936
	ds_read_b128 v[6:9], v100 offset:15952
	v_pk_fma_f32 v[110:111], v[88:89], v[74:75], v[110:111]
	v_pk_fma_f32 v[112:113], v[88:89], v[66:67], v[112:113]
	ds_read_b128 v[10:13], v100 offset:16192
	ds_read_b128 v[14:17], v100 offset:16208
	v_pk_fma_f32 v[110:111], v[90:91], v[76:77], v[110:111]
	v_pk_fma_f32 v[112:113], v[90:91], v[68:69], v[112:113]
	ds_read_b128 v[34:37], v100 offset:16448
	ds_read_b128 v[38:41], v100 offset:16464
	v_add_f32_e32 v140, v110, v111
	v_add_f32_e32 v141, v112, v113
	v_pk_mul_f32 v[114:115], v[84:85], v[50:51]
	v_add_f32_dpp v140, v140, v140 quad_perm:[1,0,3,2] row_mask:0xf bank_mask:0xf bound_ctrl:1
	v_add_f32_dpp v141, v141, v141 quad_perm:[1,0,3,2] row_mask:0xf bank_mask:0xf bound_ctrl:1
	v_pk_mul_f32 v[116:117], v[86:87], v[52:53]
	v_add_f32_dpp v140, v140, v140 quad_perm:[2,3,0,1] row_mask:0xf bank_mask:0xf bound_ctrl:1
	v_add_f32_dpp v141, v141, v141 quad_perm:[2,3,0,1] row_mask:0xf bank_mask:0xf bound_ctrl:1
	v_pk_mul_f32 v[118:119], v[88:89], v[46:47]
	v_add_f32_dpp v140, v140, v140 row_half_mirror row_mask:0xf bank_mask:0xf bound_ctrl:1
	v_add_f32_dpp v141, v141, v141 row_half_mirror row_mask:0xf bank_mask:0xf bound_ctrl:1
	v_pk_mul_f32 v[120:121], v[90:91], v[48:49]
	ds_read_b128 v[26:29], v100 offset:16704
	ds_read_b128 v[30:33], v100 offset:16720
	v_mul_f32_e32 v142, v140, v98
	v_mul_f32_e32 v143, v99, v0
	ds_read_b32 v94, v101 offset:16960
	v_add_f32_e32 v141, v142, v141
	ds_read_b64 v[96:97], v1 offset:17216
	v_add_f32_e32 v141, v143, v141
	v_pk_fma_f32 v[114:115], v[140:141], v[62:63], v[114:115] op_sel_hi:[0,1,1]
	v_pk_fma_f32 v[116:117], v[140:141], v[64:65], v[116:117] op_sel_hi:[0,1,1]
	v_cvt_pk_bf16_f32 v142, v141, v141
	v_pk_fma_f32 v[84:85], v[0:1], v[54:55], v[114:115] op_sel_hi:[0,1,1]
	global_store_short v153, v142, s[100:101]
	v_pk_fma_f32 v[118:119], v[140:141], v[58:59], v[118:119] op_sel_hi:[0,1,1]
	v_pk_fma_f32 v[86:87], v[0:1], v[56:57], v[116:117] op_sel_hi:[0,1,1]
	v_pk_fma_f32 v[120:121], v[140:141], v[60:61], v[120:121] op_sel_hi:[0,1,1]
	v_pk_fma_f32 v[88:89], v[0:1], v[42:43], v[118:119] op_sel_hi:[0,1,1]
	v_pk_fma_f32 v[90:91], v[0:1], v[44:45], v[120:121] op_sel_hi:[0,1,1]
	s_waitcnt lgkmcnt(0)
	v_pk_fma_f32 v[106:107], v[84:85], v[34:35], 0 op_sel_hi:[1,1,0]
	v_pk_fma_f32 v[108:109], v[84:85], v[22:23], 0 op_sel_hi:[1,1,0]
	ds_read_b128 v[70:73], v100 offset:17248
	ds_read_b128 v[66:69], v100 offset:17264
	v_pk_fma_f32 v[106:107], v[86:87], v[36:37], v[106:107]
	v_pk_fma_f32 v[108:109], v[86:87], v[24:25], v[108:109]
	ds_read_b128 v[50:53], v100 offset:17504
	ds_read_b128 v[46:49], v100 offset:17520
	v_pk_fma_f32 v[106:107], v[88:89], v[38:39], v[106:107]
	v_pk_fma_f32 v[108:109], v[88:89], v[18:19], v[108:109]
	ds_read_b128 v[54:57], v100 offset:17760
	ds_read_b128 v[42:45], v100 offset:17776
	v_pk_fma_f32 v[106:107], v[90:91], v[40:41], v[106:107]
	v_pk_fma_f32 v[108:109], v[90:91], v[20:21], v[108:109]
	ds_read_b128 v[78:81], v100 offset:18016
	ds_read_b128 v[74:77], v100 offset:18032
	v_add_f32_e32 v130, v106, v107
	v_add_f32_e32 v131, v108, v109
	v_pk_mul_f32 v[114:115], v[84:85], v[2:3]
	v_add_f32_dpp v130, v130, v130 quad_perm:[1,0,3,2] row_mask:0xf bank_mask:0xf bound_ctrl:1
	v_add_f32_dpp v131, v131, v131 quad_perm:[1,0,3,2] row_mask:0xf bank_mask:0xf bound_ctrl:1
	v_pk_mul_f32 v[116:117], v[86:87], v[4:5]
	v_add_f32_dpp v130, v130, v130 quad_perm:[2,3,0,1] row_mask:0xf bank_mask:0xf bound_ctrl:1
	v_add_f32_dpp v131, v131, v131 quad_perm:[2,3,0,1] row_mask:0xf bank_mask:0xf bound_ctrl:1
	v_pk_mul_f32 v[118:119], v[88:89], v[6:7]
	v_add_f32_dpp v130, v130, v130 row_half_mirror row_mask:0xf bank_mask:0xf bound_ctrl:1
	v_add_f32_dpp v131, v131, v131 row_half_mirror row_mask:0xf bank_mask:0xf bound_ctrl:1
	v_pk_mul_f32 v[120:121], v[90:91], v[8:9]
	ds_read_b128 v[62:65], v100 offset:18272
	ds_read_b128 v[58:61], v100 offset:18288
	v_mul_f32_e32 v132, v130, v96
	v_mul_f32_e32 v133, v97, v94
	ds_read_b32 v0, v101 offset:18528
	v_add_f32_e32 v131, v132, v131
	ds_read_b64 v[98:99], v1 offset:18784
	v_add_f32_e32 v131, v133, v131
	v_pk_fma_f32 v[114:115], v[130:131], v[26:27], v[114:115] op_sel_hi:[0,1,1]
	v_pk_fma_f32 v[116:117], v[130:131], v[28:29], v[116:117] op_sel_hi:[0,1,1]
	v_cvt_pk_bf16_f32 v132, v131, v131
	v_pk_fma_f32 v[84:85], v[94:95], v[10:11], v[114:115] op_sel_hi:[0,1,1]
	global_store_short v154, v132, s[100:101]
	v_pk_fma_f32 v[118:119], v[130:131], v[30:31], v[118:119] op_sel_hi:[0,1,1]
	v_pk_fma_f32 v[86:87], v[94:95], v[12:13], v[116:117] op_sel_hi:[0,1,1]
	v_pk_fma_f32 v[120:121], v[130:131], v[32:33], v[120:121] op_sel_hi:[0,1,1]
	v_pk_fma_f32 v[88:89], v[94:95], v[14:15], v[118:119] op_sel_hi:[0,1,1]
	v_pk_fma_f32 v[90:91], v[94:95], v[16:17], v[120:121] op_sel_hi:[0,1,1]
	s_waitcnt lgkmcnt(0)
	v_pk_fma_f32 v[110:111], v[84:85], v[78:79], 0 op_sel_hi:[1,1,0]
	v_pk_fma_f32 v[112:113], v[84:85], v[70:71], 0 op_sel_hi:[1,1,0]
	ds_read_b128 v[22:25], v100 offset:18816
	ds_read_b128 v[18:21], v100 offset:18832
	v_pk_fma_f32 v[110:111], v[86:87], v[80:81], v[110:111]
	v_pk_fma_f32 v[112:113], v[86:87], v[72:73], v[112:113]
	ds_read_b128 v[2:5], v100 offset:19072
	ds_read_b128 v[6:9], v100 offset:19088
	v_pk_fma_f32 v[110:111], v[88:89], v[74:75], v[110:111]
	v_pk_fma_f32 v[112:113], v[88:89], v[66:67], v[112:113]
	ds_read_b128 v[10:13], v100 offset:19328
	ds_read_b128 v[14:17], v100 offset:19344
	v_pk_fma_f32 v[110:111], v[90:91], v[76:77], v[110:111]
	v_pk_fma_f32 v[112:113], v[90:91], v[68:69], v[112:113]
	ds_read_b128 v[34:37], v100 offset:19584
	ds_read_b128 v[38:41], v100 offset:19600
	v_add_f32_e32 v140, v110, v111
	v_add_f32_e32 v141, v112, v113
	v_pk_mul_f32 v[114:115], v[84:85], v[50:51]
	v_add_f32_dpp v140, v140, v140 quad_perm:[1,0,3,2] row_mask:0xf bank_mask:0xf bound_ctrl:1
	v_add_f32_dpp v141, v141, v141 quad_perm:[1,0,3,2] row_mask:0xf bank_mask:0xf bound_ctrl:1
	v_pk_mul_f32 v[116:117], v[86:87], v[52:53]
	v_add_f32_dpp v140, v140, v140 quad_perm:[2,3,0,1] row_mask:0xf bank_mask:0xf bound_ctrl:1
	v_add_f32_dpp v141, v141, v141 quad_perm:[2,3,0,1] row_mask:0xf bank_mask:0xf bound_ctrl:1
	v_pk_mul_f32 v[118:119], v[88:89], v[46:47]
	v_add_f32_dpp v140, v140, v140 row_half_mirror row_mask:0xf bank_mask:0xf bound_ctrl:1
	v_add_f32_dpp v141, v141, v141 row_half_mirror row_mask:0xf bank_mask:0xf bound_ctrl:1
	v_pk_mul_f32 v[120:121], v[90:91], v[48:49]
	ds_read_b128 v[26:29], v100 offset:19840
	ds_read_b128 v[30:33], v100 offset:19856
	v_mul_f32_e32 v142, v140, v98
	v_mul_f32_e32 v143, v99, v0
	ds_read_b32 v94, v101 offset:20096
	v_add_f32_e32 v141, v142, v141
	ds_read_b64 v[96:97], v1 offset:20352
	v_add_f32_e32 v141, v143, v141
	v_pk_fma_f32 v[114:115], v[140:141], v[62:63], v[114:115] op_sel_hi:[0,1,1]
	v_pk_fma_f32 v[116:117], v[140:141], v[64:65], v[116:117] op_sel_hi:[0,1,1]
	v_cvt_pk_bf16_f32 v142, v141, v141
	v_pk_fma_f32 v[84:85], v[0:1], v[54:55], v[114:115] op_sel_hi:[0,1,1]
	global_store_short v155, v142, s[100:101]
	v_pk_fma_f32 v[118:119], v[140:141], v[58:59], v[118:119] op_sel_hi:[0,1,1]
	v_pk_fma_f32 v[86:87], v[0:1], v[56:57], v[116:117] op_sel_hi:[0,1,1]
	v_pk_fma_f32 v[120:121], v[140:141], v[60:61], v[120:121] op_sel_hi:[0,1,1]
	v_pk_fma_f32 v[88:89], v[0:1], v[42:43], v[118:119] op_sel_hi:[0,1,1]
	v_pk_fma_f32 v[90:91], v[0:1], v[44:45], v[120:121] op_sel_hi:[0,1,1]
	s_waitcnt lgkmcnt(0)
	v_pk_fma_f32 v[106:107], v[84:85], v[34:35], 0 op_sel_hi:[1,1,0]
	v_pk_fma_f32 v[108:109], v[84:85], v[22:23], 0 op_sel_hi:[1,1,0]
	ds_read_b128 v[70:73], v100 offset:20384
	ds_read_b128 v[66:69], v100 offset:20400
	v_pk_fma_f32 v[106:107], v[86:87], v[36:37], v[106:107]
	v_pk_fma_f32 v[108:109], v[86:87], v[24:25], v[108:109]
	ds_read_b128 v[50:53], v100 offset:20640
	ds_read_b128 v[46:49], v100 offset:20656
	v_pk_fma_f32 v[106:107], v[88:89], v[38:39], v[106:107]
	v_pk_fma_f32 v[108:109], v[88:89], v[18:19], v[108:109]
	ds_read_b128 v[54:57], v100 offset:20896
	ds_read_b128 v[42:45], v100 offset:20912
	v_pk_fma_f32 v[106:107], v[90:91], v[40:41], v[106:107]
	v_pk_fma_f32 v[108:109], v[90:91], v[20:21], v[108:109]
	ds_read_b128 v[78:81], v100 offset:21152
	ds_read_b128 v[74:77], v100 offset:21168
	v_add_f32_e32 v130, v106, v107
	v_add_f32_e32 v131, v108, v109
	v_pk_mul_f32 v[114:115], v[84:85], v[2:3]
	v_add_f32_dpp v130, v130, v130 quad_perm:[1,0,3,2] row_mask:0xf bank_mask:0xf bound_ctrl:1
	v_add_f32_dpp v131, v131, v131 quad_perm:[1,0,3,2] row_mask:0xf bank_mask:0xf bound_ctrl:1
	v_pk_mul_f32 v[116:117], v[86:87], v[4:5]
	v_add_f32_dpp v130, v130, v130 quad_perm:[2,3,0,1] row_mask:0xf bank_mask:0xf bound_ctrl:1
	v_add_f32_dpp v131, v131, v131 quad_perm:[2,3,0,1] row_mask:0xf bank_mask:0xf bound_ctrl:1
	v_pk_mul_f32 v[118:119], v[88:89], v[6:7]
	v_add_f32_dpp v130, v130, v130 row_half_mirror row_mask:0xf bank_mask:0xf bound_ctrl:1
	v_add_f32_dpp v131, v131, v131 row_half_mirror row_mask:0xf bank_mask:0xf bound_ctrl:1
	v_pk_mul_f32 v[120:121], v[90:91], v[8:9]
	ds_read_b128 v[62:65], v100 offset:21408
	ds_read_b128 v[58:61], v100 offset:21424
	v_mul_f32_e32 v132, v130, v96
	v_mul_f32_e32 v133, v97, v94
	ds_read_b32 v0, v101 offset:21664
	v_add_f32_e32 v131, v132, v131
	ds_read_b64 v[98:99], v1 offset:21920
	v_add_f32_e32 v131, v133, v131
	v_pk_fma_f32 v[114:115], v[130:131], v[26:27], v[114:115] op_sel_hi:[0,1,1]
	v_pk_fma_f32 v[116:117], v[130:131], v[28:29], v[116:117] op_sel_hi:[0,1,1]
	v_cvt_pk_bf16_f32 v132, v131, v131
	v_pk_fma_f32 v[84:85], v[94:95], v[10:11], v[114:115] op_sel_hi:[0,1,1]
	global_store_short v156, v132, s[100:101]
	v_pk_fma_f32 v[118:119], v[130:131], v[30:31], v[118:119] op_sel_hi:[0,1,1]
	v_pk_fma_f32 v[86:87], v[94:95], v[12:13], v[116:117] op_sel_hi:[0,1,1]
	v_pk_fma_f32 v[120:121], v[130:131], v[32:33], v[120:121] op_sel_hi:[0,1,1]
	v_pk_fma_f32 v[88:89], v[94:95], v[14:15], v[118:119] op_sel_hi:[0,1,1]
	v_pk_fma_f32 v[90:91], v[94:95], v[16:17], v[120:121] op_sel_hi:[0,1,1]
	s_waitcnt lgkmcnt(0)
	v_pk_fma_f32 v[110:111], v[84:85], v[78:79], 0 op_sel_hi:[1,1,0]
	v_pk_fma_f32 v[112:113], v[84:85], v[70:71], 0 op_sel_hi:[1,1,0]
	ds_read_b128 v[22:25], v100 offset:21952
	ds_read_b128 v[18:21], v100 offset:21968
	v_pk_fma_f32 v[110:111], v[86:87], v[80:81], v[110:111]
	v_pk_fma_f32 v[112:113], v[86:87], v[72:73], v[112:113]
	ds_read_b128 v[2:5], v100 offset:22208
	ds_read_b128 v[6:9], v100 offset:22224
	v_pk_fma_f32 v[110:111], v[88:89], v[74:75], v[110:111]
	v_pk_fma_f32 v[112:113], v[88:89], v[66:67], v[112:113]
	ds_read_b128 v[10:13], v100 offset:22464
	ds_read_b128 v[14:17], v100 offset:22480
	v_pk_fma_f32 v[110:111], v[90:91], v[76:77], v[110:111]
	v_pk_fma_f32 v[112:113], v[90:91], v[68:69], v[112:113]
	ds_read_b128 v[34:37], v100 offset:22720
	ds_read_b128 v[38:41], v100 offset:22736
	v_add_f32_e32 v140, v110, v111
	v_add_f32_e32 v141, v112, v113
	v_pk_mul_f32 v[114:115], v[84:85], v[50:51]
	v_add_f32_dpp v140, v140, v140 quad_perm:[1,0,3,2] row_mask:0xf bank_mask:0xf bound_ctrl:1
	v_add_f32_dpp v141, v141, v141 quad_perm:[1,0,3,2] row_mask:0xf bank_mask:0xf bound_ctrl:1
	v_pk_mul_f32 v[116:117], v[86:87], v[52:53]
	v_add_f32_dpp v140, v140, v140 quad_perm:[2,3,0,1] row_mask:0xf bank_mask:0xf bound_ctrl:1
	v_add_f32_dpp v141, v141, v141 quad_perm:[2,3,0,1] row_mask:0xf bank_mask:0xf bound_ctrl:1
	v_pk_mul_f32 v[118:119], v[88:89], v[46:47]
	v_add_f32_dpp v140, v140, v140 row_half_mirror row_mask:0xf bank_mask:0xf bound_ctrl:1
	v_add_f32_dpp v141, v141, v141 row_half_mirror row_mask:0xf bank_mask:0xf bound_ctrl:1
	v_pk_mul_f32 v[120:121], v[90:91], v[48:49]
	ds_read_b128 v[26:29], v100 offset:22976
	ds_read_b128 v[30:33], v100 offset:22992
	v_mul_f32_e32 v142, v140, v98
	v_mul_f32_e32 v143, v99, v0
	ds_read_b32 v94, v101 offset:23232
	v_add_f32_e32 v141, v142, v141
	ds_read_b64 v[96:97], v1 offset:23488
	v_add_f32_e32 v141, v143, v141
	v_pk_fma_f32 v[114:115], v[140:141], v[62:63], v[114:115] op_sel_hi:[0,1,1]
	v_pk_fma_f32 v[116:117], v[140:141], v[64:65], v[116:117] op_sel_hi:[0,1,1]
	v_cvt_pk_bf16_f32 v142, v141, v141
	v_pk_fma_f32 v[84:85], v[0:1], v[54:55], v[114:115] op_sel_hi:[0,1,1]
	global_store_short v157, v142, s[100:101]
	v_pk_fma_f32 v[118:119], v[140:141], v[58:59], v[118:119] op_sel_hi:[0,1,1]
	v_pk_fma_f32 v[86:87], v[0:1], v[56:57], v[116:117] op_sel_hi:[0,1,1]
	v_pk_fma_f32 v[120:121], v[140:141], v[60:61], v[120:121] op_sel_hi:[0,1,1]
	v_pk_fma_f32 v[88:89], v[0:1], v[42:43], v[118:119] op_sel_hi:[0,1,1]
	v_pk_fma_f32 v[90:91], v[0:1], v[44:45], v[120:121] op_sel_hi:[0,1,1]
	s_waitcnt lgkmcnt(0)
	v_pk_fma_f32 v[106:107], v[84:85], v[34:35], 0 op_sel_hi:[1,1,0]
	v_pk_fma_f32 v[108:109], v[84:85], v[22:23], 0 op_sel_hi:[1,1,0]
	ds_read_b128 v[70:73], v100 offset:23520
	ds_read_b128 v[66:69], v100 offset:23536
	v_pk_fma_f32 v[106:107], v[86:87], v[36:37], v[106:107]
	v_pk_fma_f32 v[108:109], v[86:87], v[24:25], v[108:109]
	ds_read_b128 v[50:53], v100 offset:23776
	ds_read_b128 v[46:49], v100 offset:23792
	v_pk_fma_f32 v[106:107], v[88:89], v[38:39], v[106:107]
	v_pk_fma_f32 v[108:109], v[88:89], v[18:19], v[108:109]
	ds_read_b128 v[54:57], v100 offset:24032
	ds_read_b128 v[42:45], v100 offset:24048
	v_pk_fma_f32 v[106:107], v[90:91], v[40:41], v[106:107]
	v_pk_fma_f32 v[108:109], v[90:91], v[20:21], v[108:109]
	ds_read_b128 v[78:81], v100 offset:24288
	ds_read_b128 v[74:77], v100 offset:24304
	v_add_f32_e32 v130, v106, v107
	v_add_f32_e32 v131, v108, v109
	v_pk_mul_f32 v[114:115], v[84:85], v[2:3]
	v_add_f32_dpp v130, v130, v130 quad_perm:[1,0,3,2] row_mask:0xf bank_mask:0xf bound_ctrl:1
	v_add_f32_dpp v131, v131, v131 quad_perm:[1,0,3,2] row_mask:0xf bank_mask:0xf bound_ctrl:1
	v_pk_mul_f32 v[116:117], v[86:87], v[4:5]
	v_add_f32_dpp v130, v130, v130 quad_perm:[2,3,0,1] row_mask:0xf bank_mask:0xf bound_ctrl:1
	v_add_f32_dpp v131, v131, v131 quad_perm:[2,3,0,1] row_mask:0xf bank_mask:0xf bound_ctrl:1
	v_pk_mul_f32 v[118:119], v[88:89], v[6:7]
	v_add_f32_dpp v130, v130, v130 row_half_mirror row_mask:0xf bank_mask:0xf bound_ctrl:1
	v_add_f32_dpp v131, v131, v131 row_half_mirror row_mask:0xf bank_mask:0xf bound_ctrl:1
	v_pk_mul_f32 v[120:121], v[90:91], v[8:9]
	ds_read_b128 v[62:65], v100 offset:24544
	ds_read_b128 v[58:61], v100 offset:24560
	v_mul_f32_e32 v132, v130, v96
	v_mul_f32_e32 v133, v97, v94
	ds_read_b32 v0, v101 offset:24800
	v_add_f32_e32 v131, v132, v131
	ds_read_b64 v[98:99], v1 offset:25056
	v_add_f32_e32 v131, v133, v131
	v_pk_fma_f32 v[114:115], v[130:131], v[26:27], v[114:115] op_sel_hi:[0,1,1]
	v_pk_fma_f32 v[116:117], v[130:131], v[28:29], v[116:117] op_sel_hi:[0,1,1]
	v_cvt_pk_bf16_f32 v132, v131, v131
	v_pk_fma_f32 v[84:85], v[94:95], v[10:11], v[114:115] op_sel_hi:[0,1,1]
	global_store_short v158, v132, s[100:101]
	v_pk_fma_f32 v[118:119], v[130:131], v[30:31], v[118:119] op_sel_hi:[0,1,1]
	v_pk_fma_f32 v[86:87], v[94:95], v[12:13], v[116:117] op_sel_hi:[0,1,1]
	v_pk_fma_f32 v[120:121], v[130:131], v[32:33], v[120:121] op_sel_hi:[0,1,1]
	v_pk_fma_f32 v[88:89], v[94:95], v[14:15], v[118:119] op_sel_hi:[0,1,1]
	v_pk_fma_f32 v[90:91], v[94:95], v[16:17], v[120:121] op_sel_hi:[0,1,1]
	s_waitcnt lgkmcnt(0)
	v_pk_fma_f32 v[110:111], v[84:85], v[78:79], 0 op_sel_hi:[1,1,0]
	v_pk_fma_f32 v[112:113], v[84:85], v[70:71], 0 op_sel_hi:[1,1,0]
	v_pk_fma_f32 v[110:111], v[86:87], v[80:81], v[110:111]
	v_pk_fma_f32 v[112:113], v[86:87], v[72:73], v[112:113]
	v_pk_fma_f32 v[110:111], v[88:89], v[74:75], v[110:111]
	v_pk_fma_f32 v[112:113], v[88:89], v[66:67], v[112:113]
	v_pk_fma_f32 v[110:111], v[90:91], v[76:77], v[110:111]
	v_pk_fma_f32 v[112:113], v[90:91], v[68:69], v[112:113]
	v_add_f32_e32 v140, v110, v111
	v_add_f32_e32 v141, v112, v113
	v_pk_mul_f32 v[114:115], v[84:85], v[50:51]
	v_add_f32_dpp v140, v140, v140 quad_perm:[1,0,3,2] row_mask:0xf bank_mask:0xf bound_ctrl:1
	v_add_f32_dpp v141, v141, v141 quad_perm:[1,0,3,2] row_mask:0xf bank_mask:0xf bound_ctrl:1
	v_pk_mul_f32 v[116:117], v[86:87], v[52:53]
	v_add_f32_dpp v140, v140, v140 quad_perm:[2,3,0,1] row_mask:0xf bank_mask:0xf bound_ctrl:1
	v_add_f32_dpp v141, v141, v141 quad_perm:[2,3,0,1] row_mask:0xf bank_mask:0xf bound_ctrl:1
	v_pk_mul_f32 v[118:119], v[88:89], v[46:47]
	v_add_f32_dpp v140, v140, v140 row_half_mirror row_mask:0xf bank_mask:0xf bound_ctrl:1
	v_add_f32_dpp v141, v141, v141 row_half_mirror row_mask:0xf bank_mask:0xf bound_ctrl:1
	v_pk_mul_f32 v[120:121], v[90:91], v[48:49]
	v_mul_f32_e32 v142, v140, v98
	v_mul_f32_e32 v143, v99, v0
	v_add_f32_e32 v141, v142, v141
	v_add_f32_e32 v141, v143, v141
	v_pk_fma_f32 v[114:115], v[140:141], v[62:63], v[114:115] op_sel_hi:[0,1,1]
	v_pk_fma_f32 v[116:117], v[140:141], v[64:65], v[116:117] op_sel_hi:[0,1,1]
	v_cvt_pk_bf16_f32 v142, v141, v141
	v_pk_fma_f32 v[84:85], v[0:1], v[54:55], v[114:115] op_sel_hi:[0,1,1]
	global_store_short v159, v142, s[100:101]
	v_pk_fma_f32 v[118:119], v[140:141], v[58:59], v[118:119] op_sel_hi:[0,1,1]
	v_pk_fma_f32 v[86:87], v[0:1], v[56:57], v[116:117] op_sel_hi:[0,1,1]
	v_pk_fma_f32 v[120:121], v[140:141], v[60:61], v[120:121] op_sel_hi:[0,1,1]
	v_pk_fma_f32 v[88:89], v[0:1], v[42:43], v[118:119] op_sel_hi:[0,1,1]
	v_pk_fma_f32 v[90:91], v[0:1], v[44:45], v[120:121] op_sel_hi:[0,1,1]
.LBB0_863:
	s_waitcnt lgkmcnt(0)
	s_barrier
	ds_read_b128 v[22:25], v100 offset:25088
	ds_read_b128 v[18:21], v100 offset:25104
	ds_read_b128 v[2:5], v100 offset:25344
	ds_read_b128 v[6:9], v100 offset:25360
	ds_read_b128 v[10:13], v100 offset:25600
	ds_read_b128 v[14:17], v100 offset:25616
	ds_read_b128 v[34:37], v100 offset:25856
	ds_read_b128 v[38:41], v100 offset:25872
	ds_read_b128 v[26:29], v100 offset:26112
	ds_read_b128 v[30:33], v100 offset:26128
	ds_read_b32 v94, v101 offset:26368
	ds_read_b64 v[96:97], v1 offset:26624
	v_readlane_b32 s2, v254, 61
	s_lshl_b32 s2, s2, 4
	s_add_i32 s18, s46, s2

.LBB0_869:
	s_nop 0
	v_readfirstlane_b32 s100, v92
	v_readfirstlane_b32 s101, v93
	s_sub_u32 s100, s100, m0
	s_subb_u32 s101, s101, 0
	s_waitcnt lgkmcnt(0)
	v_pk_fma_f32 v[106:107], v[84:85], v[34:35], 0 op_sel_hi:[1,1,0]
	v_pk_fma_f32 v[108:109], v[84:85], v[22:23], 0 op_sel_hi:[1,1,0]
	ds_read_b128 v[70:73], v100 offset:26656
	ds_read_b128 v[66:69], v100 offset:26672
	v_pk_fma_f32 v[106:107], v[86:87], v[36:37], v[106:107]
	v_pk_fma_f32 v[108:109], v[86:87], v[24:25], v[108:109]
	ds_read_b128 v[50:53], v100 offset:26912
	ds_read_b128 v[46:49], v100 offset:26928
	v_pk_fma_f32 v[106:107], v[88:89], v[38:39], v[106:107]
	v_pk_fma_f32 v[108:109], v[88:89], v[18:19], v[108:109]
	ds_read_b128 v[54:57], v100 offset:27168
	ds_read_b128 v[42:45], v100 offset:27184
	v_pk_fma_f32 v[106:107], v[90:91], v[40:41], v[106:107]
	v_pk_fma_f32 v[108:109], v[90:91], v[20:21], v[108:109]
	ds_read_b128 v[78:81], v100 offset:27424
	ds_read_b128 v[74:77], v100 offset:27440
	v_add_f32_e32 v130, v106, v107
	v_add_f32_e32 v131, v108, v109
	v_pk_mul_f32 v[114:115], v[84:85], v[2:3]
	v_add_f32_dpp v130, v130, v130 quad_perm:[1,0,3,2] row_mask:0xf bank_mask:0xf bound_ctrl:1
	v_add_f32_dpp v131, v131, v131 quad_perm:[1,0,3,2] row_mask:0xf bank_mask:0xf bound_ctrl:1
	v_pk_mul_f32 v[116:117], v[86:87], v[4:5]
	v_add_f32_dpp v130, v130, v130 quad_perm:[2,3,0,1] row_mask:0xf bank_mask:0xf bound_ctrl:1
	v_add_f32_dpp v131, v131, v131 quad_perm:[2,3,0,1] row_mask:0xf bank_mask:0xf bound_ctrl:1
	v_pk_mul_f32 v[118:119], v[88:89], v[6:7]
	v_add_f32_dpp v130, v130, v130 row_half_mirror row_mask:0xf bank_mask:0xf bound_ctrl:1
	v_add_f32_dpp v131, v131, v131 row_half_mirror row_mask:0xf bank_mask:0xf bound_ctrl:1
	v_pk_mul_f32 v[120:121], v[90:91], v[8:9]
	ds_read_b128 v[62:65], v100 offset:27680
	ds_read_b128 v[58:61], v100 offset:27696
	v_mul_f32_e32 v132, v130, v96
	v_mul_f32_e32 v133, v97, v94
	ds_read_b32 v0, v101 offset:27936
	v_add_f32_e32 v131, v132, v131
	ds_read_b64 v[98:99], v1 offset:28192
	v_add_f32_e32 v131, v133, v131
	v_pk_fma_f32 v[114:115], v[130:131], v[26:27], v[114:115] op_sel_hi:[0,1,1]
	v_pk_fma_f32 v[116:117], v[130:131], v[28:29], v[116:117] op_sel_hi:[0,1,1]
	v_cvt_pk_bf16_f32 v132, v131, v131
	v_pk_fma_f32 v[84:85], v[94:95], v[10:11], v[114:115] op_sel_hi:[0,1,1]
	global_store_short v144, v132, s[100:101]
	v_pk_fma_f32 v[118:119], v[130:131], v[30:31], v[118:119] op_sel_hi:[0,1,1]
	v_pk_fma_f32 v[86:87], v[94:95], v[12:13], v[116:117] op_sel_hi:[0,1,1]
	v_pk_fma_f32 v[120:121], v[130:131], v[32:33], v[120:121] op_sel_hi:[0,1,1]
	v_pk_fma_f32 v[88:89], v[94:95], v[14:15], v[118:119] op_sel_hi:[0,1,1]
	v_pk_fma_f32 v[90:91], v[94:95], v[16:17], v[120:121] op_sel_hi:[0,1,1]
	s_waitcnt lgkmcnt(0)
	v_pk_fma_f32 v[110:111], v[84:85], v[78:79], 0 op_sel_hi:[1,1,0]
	v_pk_fma_f32 v[112:113], v[84:85], v[70:71], 0 op_sel_hi:[1,1,0]
	ds_read_b128 v[22:25], v100 offset:28224
	ds_read_b128 v[18:21], v100 offset:28240
	v_pk_fma_f32 v[110:111], v[86:87], v[80:81], v[110:111]
	v_pk_fma_f32 v[112:113], v[86:87], v[72:73], v[112:113]
	ds_read_b128 v[2:5], v100 offset:28480
	ds_read_b128 v[6:9], v100 offset:28496
	v_pk_fma_f32 v[110:111], v[88:89], v[74:75], v[110:111]
	v_pk_fma_f32 v[112:113], v[88:89], v[66:67], v[112:113]
	ds_read_b128 v[10:13], v100 offset:28736
	ds_read_b128 v[14:17], v100 offset:28752
	v_pk_fma_f32 v[110:111], v[90:91], v[76:77], v[110:111]
	v_pk_fma_f32 v[112:113], v[90:91], v[68:69], v[112:113]
	ds_read_b128 v[34:37], v100 offset:28992
	ds_read_b128 v[38:41], v100 offset:29008
	v_add_f32_e32 v140, v110, v111
	v_add_f32_e32 v141, v112, v113
	v_pk_mul_f32 v[114:115], v[84:85], v[50:51]
	v_add_f32_dpp v140, v140, v140 quad_perm:[1,0,3,2] row_mask:0xf bank_mask:0xf bound_ctrl:1
	v_add_f32_dpp v141, v141, v141 quad_perm:[1,0,3,2] row_mask:0xf bank_mask:0xf bound_ctrl:1
	v_pk_mul_f32 v[116:117], v[86:87], v[52:53]
	v_add_f32_dpp v140, v140, v140 quad_perm:[2,3,0,1] row_mask:0xf bank_mask:0xf bound_ctrl:1
	v_add_f32_dpp v141, v141, v141 quad_perm:[2,3,0,1] row_mask:0xf bank_mask:0xf bound_ctrl:1
	v_pk_mul_f32 v[118:119], v[88:89], v[46:47]
	v_add_f32_dpp v140, v140, v140 row_half_mirror row_mask:0xf bank_mask:0xf bound_ctrl:1
	v_add_f32_dpp v141, v141, v141 row_half_mirror row_mask:0xf bank_mask:0xf bound_ctrl:1
	v_pk_mul_f32 v[120:121], v[90:91], v[48:49]
	ds_read_b128 v[26:29], v100 offset:29248
	ds_read_b128 v[30:33], v100 offset:29264
	v_mul_f32_e32 v142, v140, v98
	v_mul_f32_e32 v143, v99, v0
	ds_read_b32 v94, v101 offset:29504
	v_add_f32_e32 v141, v142, v141
	ds_read_b64 v[96:97], v1 offset:29760
	v_add_f32_e32 v141, v143, v141
	v_pk_fma_f32 v[114:115], v[140:141], v[62:63], v[114:115] op_sel_hi:[0,1,1]
	v_pk_fma_f32 v[116:117], v[140:141], v[64:65], v[116:117] op_sel_hi:[0,1,1]
	v_cvt_pk_bf16_f32 v142, v141, v141
	v_pk_fma_f32 v[84:85], v[0:1], v[54:55], v[114:115] op_sel_hi:[0,1,1]
	global_store_short v145, v142, s[100:101]
	v_pk_fma_f32 v[118:119], v[140:141], v[58:59], v[118:119] op_sel_hi:[0,1,1]
	v_pk_fma_f32 v[86:87], v[0:1], v[56:57], v[116:117] op_sel_hi:[0,1,1]
	v_pk_fma_f32 v[120:121], v[140:141], v[60:61], v[120:121] op_sel_hi:[0,1,1]
	v_pk_fma_f32 v[88:89], v[0:1], v[42:43], v[118:119] op_sel_hi:[0,1,1]
	v_pk_fma_f32 v[90:91], v[0:1], v[44:45], v[120:121] op_sel_hi:[0,1,1]
	s_waitcnt lgkmcnt(0)
	v_pk_fma_f32 v[106:107], v[84:85], v[34:35], 0 op_sel_hi:[1,1,0]
	v_pk_fma_f32 v[108:109], v[84:85], v[22:23], 0 op_sel_hi:[1,1,0]
	ds_read_b128 v[70:73], v100 offset:29792
	ds_read_b128 v[66:69], v100 offset:29808
	v_pk_fma_f32 v[106:107], v[86:87], v[36:37], v[106:107]
	v_pk_fma_f32 v[108:109], v[86:87], v[24:25], v[108:109]
	ds_read_b128 v[50:53], v100 offset:30048
	ds_read_b128 v[46:49], v100 offset:30064
	v_pk_fma_f32 v[106:107], v[88:89], v[38:39], v[106:107]
	v_pk_fma_f32 v[108:109], v[88:89], v[18:19], v[108:109]
	ds_read_b128 v[54:57], v100 offset:30304
	ds_read_b128 v[42:45], v100 offset:30320
	v_pk_fma_f32 v[106:107], v[90:91], v[40:41], v[106:107]
	v_pk_fma_f32 v[108:109], v[90:91], v[20:21], v[108:109]
	ds_read_b128 v[78:81], v100 offset:30560
	ds_read_b128 v[74:77], v100 offset:30576
	v_add_f32_e32 v130, v106, v107
	v_add_f32_e32 v131, v108, v109
	v_pk_mul_f32 v[114:115], v[84:85], v[2:3]
	v_add_f32_dpp v130, v130, v130 quad_perm:[1,0,3,2] row_mask:0xf bank_mask:0xf bound_ctrl:1
	v_add_f32_dpp v131, v131, v131 quad_perm:[1,0,3,2] row_mask:0xf bank_mask:0xf bound_ctrl:1
	v_pk_mul_f32 v[116:117], v[86:87], v[4:5]
	v_add_f32_dpp v130, v130, v130 quad_perm:[2,3,0,1] row_mask:0xf bank_mask:0xf bound_ctrl:1
	v_add_f32_dpp v131, v131, v131 quad_perm:[2,3,0,1] row_mask:0xf bank_mask:0xf bound_ctrl:1
	v_pk_mul_f32 v[118:119], v[88:89], v[6:7]
	v_add_f32_dpp v130, v130, v130 row_half_mirror row_mask:0xf bank_mask:0xf bound_ctrl:1
	v_add_f32_dpp v131, v131, v131 row_half_mirror row_mask:0xf bank_mask:0xf bound_ctrl:1
	v_pk_mul_f32 v[120:121], v[90:91], v[8:9]
	ds_read_b128 v[62:65], v100 offset:30816
	ds_read_b128 v[58:61], v100 offset:30832
	v_mul_f32_e32 v132, v130, v96
	v_mul_f32_e32 v133, v97, v94
	ds_read_b32 v0, v101 offset:31072
	v_add_f32_e32 v131, v132, v131
	ds_read_b64 v[98:99], v1 offset:31328
	v_add_f32_e32 v131, v133, v131
	v_pk_fma_f32 v[114:115], v[130:131], v[26:27], v[114:115] op_sel_hi:[0,1,1]
	v_pk_fma_f32 v[116:117], v[130:131], v[28:29], v[116:117] op_sel_hi:[0,1,1]
	v_cvt_pk_bf16_f32 v132, v131, v131
	v_pk_fma_f32 v[84:85], v[94:95], v[10:11], v[114:115] op_sel_hi:[0,1,1]
	global_store_short v146, v132, s[100:101]
	v_pk_fma_f32 v[118:119], v[130:131], v[30:31], v[118:119] op_sel_hi:[0,1,1]
	v_pk_fma_f32 v[86:87], v[94:95], v[12:13], v[116:117] op_sel_hi:[0,1,1]
	v_pk_fma_f32 v[120:121], v[130:131], v[32:33], v[120:121] op_sel_hi:[0,1,1]
	v_pk_fma_f32 v[88:89], v[94:95], v[14:15], v[118:119] op_sel_hi:[0,1,1]
	v_pk_fma_f32 v[90:91], v[94:95], v[16:17], v[120:121] op_sel_hi:[0,1,1]
	s_waitcnt lgkmcnt(0)
	v_pk_fma_f32 v[110:111], v[84:85], v[78:79], 0 op_sel_hi:[1,1,0]
	v_pk_fma_f32 v[112:113], v[84:85], v[70:71], 0 op_sel_hi:[1,1,0]
	ds_read_b128 v[22:25], v100 offset:31360
	ds_read_b128 v[18:21], v100 offset:31376
	v_pk_fma_f32 v[110:111], v[86:87], v[80:81], v[110:111]
	v_pk_fma_f32 v[112:113], v[86:87], v[72:73], v[112:113]
	ds_read_b128 v[2:5], v100 offset:31616
	ds_read_b128 v[6:9], v100 offset:31632
	v_pk_fma_f32 v[110:111], v[88:89], v[74:75], v[110:111]
	v_pk_fma_f32 v[112:113], v[88:89], v[66:67], v[112:113]
	ds_read_b128 v[10:13], v100 offset:31872
	ds_read_b128 v[14:17], v100 offset:31888
	v_pk_fma_f32 v[110:111], v[90:91], v[76:77], v[110:111]
	v_pk_fma_f32 v[112:113], v[90:91], v[68:69], v[112:113]
	ds_read_b128 v[34:37], v100 offset:32128
	ds_read_b128 v[38:41], v100 offset:32144
	v_add_f32_e32 v140, v110, v111
	v_add_f32_e32 v141, v112, v113
	v_pk_mul_f32 v[114:115], v[84:85], v[50:51]
	v_add_f32_dpp v140, v140, v140 quad_perm:[1,0,3,2] row_mask:0xf bank_mask:0xf bound_ctrl:1
	v_add_f32_dpp v141, v141, v141 quad_perm:[1,0,3,2] row_mask:0xf bank_mask:0xf bound_ctrl:1
	v_pk_mul_f32 v[116:117], v[86:87], v[52:53]
	v_add_f32_dpp v140, v140, v140 quad_perm:[2,3,0,1] row_mask:0xf bank_mask:0xf bound_ctrl:1
	v_add_f32_dpp v141, v141, v141 quad_perm:[2,3,0,1] row_mask:0xf bank_mask:0xf bound_ctrl:1
	v_pk_mul_f32 v[118:119], v[88:89], v[46:47]
	v_add_f32_dpp v140, v140, v140 row_half_mirror row_mask:0xf bank_mask:0xf bound_ctrl:1
	v_add_f32_dpp v141, v141, v141 row_half_mirror row_mask:0xf bank_mask:0xf bound_ctrl:1
	v_pk_mul_f32 v[120:121], v[90:91], v[48:49]
	ds_read_b128 v[26:29], v100 offset:32384
	ds_read_b128 v[30:33], v100 offset:32400
	v_mul_f32_e32 v142, v140, v98
	v_mul_f32_e32 v143, v99, v0
	ds_read_b32 v94, v101 offset:32640
	v_add_f32_e32 v141, v142, v141
	ds_read_b64 v[96:97], v1 offset:32896
	v_add_f32_e32 v141, v143, v141
	v_pk_fma_f32 v[114:115], v[140:141], v[62:63], v[114:115] op_sel_hi:[0,1,1]
	v_pk_fma_f32 v[116:117], v[140:141], v[64:65], v[116:117] op_sel_hi:[0,1,1]
	v_cvt_pk_bf16_f32 v142, v141, v141
	v_pk_fma_f32 v[84:85], v[0:1], v[54:55], v[114:115] op_sel_hi:[0,1,1]
	global_store_short v147, v142, s[100:101]
	v_pk_fma_f32 v[118:119], v[140:141], v[58:59], v[118:119] op_sel_hi:[0,1,1]
	v_pk_fma_f32 v[86:87], v[0:1], v[56:57], v[116:117] op_sel_hi:[0,1,1]
	v_pk_fma_f32 v[120:121], v[140:141], v[60:61], v[120:121] op_sel_hi:[0,1,1]
	v_pk_fma_f32 v[88:89], v[0:1], v[42:43], v[118:119] op_sel_hi:[0,1,1]
	v_pk_fma_f32 v[90:91], v[0:1], v[44:45], v[120:121] op_sel_hi:[0,1,1]
	s_waitcnt lgkmcnt(0)
	v_pk_fma_f32 v[106:107], v[84:85], v[34:35], 0 op_sel_hi:[1,1,0]
	v_pk_fma_f32 v[108:109], v[84:85], v[22:23], 0 op_sel_hi:[1,1,0]
	ds_read_b128 v[70:73], v100 offset:32928
	ds_read_b128 v[66:69], v100 offset:32944
	v_pk_fma_f32 v[106:107], v[86:87], v[36:37], v[106:107]
	v_pk_fma_f32 v[108:109], v[86:87], v[24:25], v[108:109]
	ds_read_b128 v[50:53], v100 offset:33184
	ds_read_b128 v[46:49], v100 offset:33200
	v_pk_fma_f32 v[106:107], v[88:89], v[38:39], v[106:107]
	v_pk_fma_f32 v[108:109], v[88:89], v[18:19], v[108:109]
	ds_read_b128 v[54:57], v100 offset:33440
	ds_read_b128 v[42:45], v100 offset:33456
	v_pk_fma_f32 v[106:107], v[90:91], v[40:41], v[106:107]
	v_pk_fma_f32 v[108:109], v[90:91], v[20:21], v[108:109]
	ds_read_b128 v[78:81], v100 offset:33696
	ds_read_b128 v[74:77], v100 offset:33712
	v_add_f32_e32 v130, v106, v107
	v_add_f32_e32 v131, v108, v109
	v_pk_mul_f32 v[114:115], v[84:85], v[2:3]
	v_add_f32_dpp v130, v130, v130 quad_perm:[1,0,3,2] row_mask:0xf bank_mask:0xf bound_ctrl:1
	v_add_f32_dpp v131, v131, v131 quad_perm:[1,0,3,2] row_mask:0xf bank_mask:0xf bound_ctrl:1
	v_pk_mul_f32 v[116:117], v[86:87], v[4:5]
	v_add_f32_dpp v130, v130, v130 quad_perm:[2,3,0,1] row_mask:0xf bank_mask:0xf bound_ctrl:1
	v_add_f32_dpp v131, v131, v131 quad_perm:[2,3,0,1] row_mask:0xf bank_mask:0xf bound_ctrl:1
	v_pk_mul_f32 v[118:119], v[88:89], v[6:7]
	v_add_f32_dpp v130, v130, v130 row_half_mirror row_mask:0xf bank_mask:0xf bound_ctrl:1
	v_add_f32_dpp v131, v131, v131 row_half_mirror row_mask:0xf bank_mask:0xf bound_ctrl:1
	v_pk_mul_f32 v[120:121], v[90:91], v[8:9]
	ds_read_b128 v[62:65], v100 offset:33952
	ds_read_b128 v[58:61], v100 offset:33968
	v_mul_f32_e32 v132, v130, v96
	v_mul_f32_e32 v133, v97, v94
	ds_read_b32 v0, v101 offset:34208
	v_add_f32_e32 v131, v132, v131
	ds_read_b64 v[98:99], v1 offset:34464
	v_add_f32_e32 v131, v133, v131
	v_pk_fma_f32 v[114:115], v[130:131], v[26:27], v[114:115] op_sel_hi:[0,1,1]
	v_pk_fma_f32 v[116:117], v[130:131], v[28:29], v[116:117] op_sel_hi:[0,1,1]
	v_cvt_pk_bf16_f32 v132, v131, v131
	v_pk_fma_f32 v[84:85], v[94:95], v[10:11], v[114:115] op_sel_hi:[0,1,1]
	global_store_short v148, v132, s[100:101]
	v_pk_fma_f32 v[118:119], v[130:131], v[30:31], v[118:119] op_sel_hi:[0,1,1]
	v_pk_fma_f32 v[86:87], v[94:95], v[12:13], v[116:117] op_sel_hi:[0,1,1]
	v_pk_fma_f32 v[120:121], v[130:131], v[32:33], v[120:121] op_sel_hi:[0,1,1]
	v_pk_fma_f32 v[88:89], v[94:95], v[14:15], v[118:119] op_sel_hi:[0,1,1]
	v_pk_fma_f32 v[90:91], v[94:95], v[16:17], v[120:121] op_sel_hi:[0,1,1]
	s_waitcnt lgkmcnt(0)
	v_pk_fma_f32 v[110:111], v[84:85], v[78:79], 0 op_sel_hi:[1,1,0]
	v_pk_fma_f32 v[112:113], v[84:85], v[70:71], 0 op_sel_hi:[1,1,0]
	ds_read_b128 v[22:25], v100 offset:34496
	ds_read_b128 v[18:21], v100 offset:34512
	v_pk_fma_f32 v[110:111], v[86:87], v[80:81], v[110:111]
	v_pk_fma_f32 v[112:113], v[86:87], v[72:73], v[112:113]
	ds_read_b128 v[2:5], v100 offset:34752
	ds_read_b128 v[6:9], v100 offset:34768
	v_pk_fma_f32 v[110:111], v[88:89], v[74:75], v[110:111]
	v_pk_fma_f32 v[112:113], v[88:89], v[66:67], v[112:113]
	ds_read_b128 v[10:13], v100 offset:35008
	ds_read_b128 v[14:17], v100 offset:35024
	v_pk_fma_f32 v[110:111], v[90:91], v[76:77], v[110:111]
	v_pk_fma_f32 v[112:113], v[90:91], v[68:69], v[112:113]
	ds_read_b128 v[34:37], v100 offset:35264
	ds_read_b128 v[38:41], v100 offset:35280
	v_add_f32_e32 v140, v110, v111
	v_add_f32_e32 v141, v112, v113
	v_pk_mul_f32 v[114:115], v[84:85], v[50:51]
	v_add_f32_dpp v140, v140, v140 quad_perm:[1,0,3,2] row_mask:0xf bank_mask:0xf bound_ctrl:1
	v_add_f32_dpp v141, v141, v141 quad_perm:[1,0,3,2] row_mask:0xf bank_mask:0xf bound_ctrl:1
	v_pk_mul_f32 v[116:117], v[86:87], v[52:53]
	v_add_f32_dpp v140, v140, v140 quad_perm:[2,3,0,1] row_mask:0xf bank_mask:0xf bound_ctrl:1
	v_add_f32_dpp v141, v141, v141 quad_perm:[2,3,0,1] row_mask:0xf bank_mask:0xf bound_ctrl:1
	v_pk_mul_f32 v[118:119], v[88:89], v[46:47]
	v_add_f32_dpp v140, v140, v140 row_half_mirror row_mask:0xf bank_mask:0xf bound_ctrl:1
	v_add_f32_dpp v141, v141, v141 row_half_mirror row_mask:0xf bank_mask:0xf bound_ctrl:1
	v_pk_mul_f32 v[120:121], v[90:91], v[48:49]
	ds_read_b128 v[26:29], v100 offset:35520
	ds_read_b128 v[30:33], v100 offset:35536
	v_mul_f32_e32 v142, v140, v98
	v_mul_f32_e32 v143, v99, v0
	ds_read_b32 v94, v101 offset:35776
	v_add_f32_e32 v141, v142, v141
	ds_read_b64 v[96:97], v1 offset:36032
	v_add_f32_e32 v141, v143, v141
	v_pk_fma_f32 v[114:115], v[140:141], v[62:63], v[114:115] op_sel_hi:[0,1,1]
	v_pk_fma_f32 v[116:117], v[140:141], v[64:65], v[116:117] op_sel_hi:[0,1,1]
	v_cvt_pk_bf16_f32 v142, v141, v141
	v_pk_fma_f32 v[84:85], v[0:1], v[54:55], v[114:115] op_sel_hi:[0,1,1]
	global_store_short v149, v142, s[100:101]
	v_pk_fma_f32 v[118:119], v[140:141], v[58:59], v[118:119] op_sel_hi:[0,1,1]
	v_pk_fma_f32 v[86:87], v[0:1], v[56:57], v[116:117] op_sel_hi:[0,1,1]
	v_pk_fma_f32 v[120:121], v[140:141], v[60:61], v[120:121] op_sel_hi:[0,1,1]
	v_pk_fma_f32 v[88:89], v[0:1], v[42:43], v[118:119] op_sel_hi:[0,1,1]
	v_pk_fma_f32 v[90:91], v[0:1], v[44:45], v[120:121] op_sel_hi:[0,1,1]
	s_waitcnt lgkmcnt(0)
	v_pk_fma_f32 v[106:107], v[84:85], v[34:35], 0 op_sel_hi:[1,1,0]
	v_pk_fma_f32 v[108:109], v[84:85], v[22:23], 0 op_sel_hi:[1,1,0]
	ds_read_b128 v[70:73], v100 offset:36064
	ds_read_b128 v[66:69], v100 offset:36080
	v_pk_fma_f32 v[106:107], v[86:87], v[36:37], v[106:107]
	v_pk_fma_f32 v[108:109], v[86:87], v[24:25], v[108:109]
	ds_read_b128 v[50:53], v100 offset:36320
	ds_read_b128 v[46:49], v100 offset:36336
	v_pk_fma_f32 v[106:107], v[88:89], v[38:39], v[106:107]
	v_pk_fma_f32 v[108:109], v[88:89], v[18:19], v[108:109]
	ds_read_b128 v[54:57], v100 offset:36576
	ds_read_b128 v[42:45], v100 offset:36592
	v_pk_fma_f32 v[106:107], v[90:91], v[40:41], v[106:107]
	v_pk_fma_f32 v[108:109], v[90:91], v[20:21], v[108:109]
	ds_read_b128 v[78:81], v100 offset:36832
	ds_read_b128 v[74:77], v100 offset:36848
	v_add_f32_e32 v130, v106, v107
	v_add_f32_e32 v131, v108, v109
	v_pk_mul_f32 v[114:115], v[84:85], v[2:3]
	v_add_f32_dpp v130, v130, v130 quad_perm:[1,0,3,2] row_mask:0xf bank_mask:0xf bound_ctrl:1
	v_add_f32_dpp v131, v131, v131 quad_perm:[1,0,3,2] row_mask:0xf bank_mask:0xf bound_ctrl:1
	v_pk_mul_f32 v[116:117], v[86:87], v[4:5]
	v_add_f32_dpp v130, v130, v130 quad_perm:[2,3,0,1] row_mask:0xf bank_mask:0xf bound_ctrl:1
	v_add_f32_dpp v131, v131, v131 quad_perm:[2,3,0,1] row_mask:0xf bank_mask:0xf bound_ctrl:1
	v_pk_mul_f32 v[118:119], v[88:89], v[6:7]
	v_add_f32_dpp v130, v130, v130 row_half_mirror row_mask:0xf bank_mask:0xf bound_ctrl:1
	v_add_f32_dpp v131, v131, v131 row_half_mirror row_mask:0xf bank_mask:0xf bound_ctrl:1
	v_pk_mul_f32 v[120:121], v[90:91], v[8:9]
	ds_read_b128 v[62:65], v100 offset:37088
	ds_read_b128 v[58:61], v100 offset:37104
	v_mul_f32_e32 v132, v130, v96
	v_mul_f32_e32 v133, v97, v94
	ds_read_b32 v0, v101 offset:37344
	v_add_f32_e32 v131, v132, v131
	ds_read_b64 v[98:99], v1 offset:37600
	v_add_f32_e32 v131, v133, v131
	v_pk_fma_f32 v[114:115], v[130:131], v[26:27], v[114:115] op_sel_hi:[0,1,1]
	v_pk_fma_f32 v[116:117], v[130:131], v[28:29], v[116:117] op_sel_hi:[0,1,1]
	v_cvt_pk_bf16_f32 v132, v131, v131
	v_pk_fma_f32 v[84:85], v[94:95], v[10:11], v[114:115] op_sel_hi:[0,1,1]
	global_store_short v150, v132, s[100:101]
	v_pk_fma_f32 v[118:119], v[130:131], v[30:31], v[118:119] op_sel_hi:[0,1,1]
	v_pk_fma_f32 v[86:87], v[94:95], v[12:13], v[116:117] op_sel_hi:[0,1,1]
	v_pk_fma_f32 v[120:121], v[130:131], v[32:33], v[120:121] op_sel_hi:[0,1,1]
	v_pk_fma_f32 v[88:89], v[94:95], v[14:15], v[118:119] op_sel_hi:[0,1,1]
	v_pk_fma_f32 v[90:91], v[94:95], v[16:17], v[120:121] op_sel_hi:[0,1,1]
	s_waitcnt lgkmcnt(0)
	v_pk_fma_f32 v[110:111], v[84:85], v[78:79], 0 op_sel_hi:[1,1,0]
	v_pk_fma_f32 v[112:113], v[84:85], v[70:71], 0 op_sel_hi:[1,1,0]
	ds_read_b128 v[22:25], v100 offset:37632
	ds_read_b128 v[18:21], v100 offset:37648
	v_pk_fma_f32 v[110:111], v[86:87], v[80:81], v[110:111]
	v_pk_fma_f32 v[112:113], v[86:87], v[72:73], v[112:113]
	ds_read_b128 v[2:5], v100 offset:37888
	ds_read_b128 v[6:9], v100 offset:37904
	v_pk_fma_f32 v[110:111], v[88:89], v[74:75], v[110:111]
	v_pk_fma_f32 v[112:113], v[88:89], v[66:67], v[112:113]
	ds_read_b128 v[10:13], v100 offset:38144
	ds_read_b128 v[14:17], v100 offset:38160
	v_pk_fma_f32 v[110:111], v[90:91], v[76:77], v[110:111]
	v_pk_fma_f32 v[112:113], v[90:91], v[68:69], v[112:113]
	ds_read_b128 v[34:37], v100 offset:38400
	ds_read_b128 v[38:41], v100 offset:38416
	v_add_f32_e32 v140, v110, v111
	v_add_f32_e32 v141, v112, v113
	v_pk_mul_f32 v[114:115], v[84:85], v[50:51]
	v_add_f32_dpp v140, v140, v140 quad_perm:[1,0,3,2] row_mask:0xf bank_mask:0xf bound_ctrl:1
	v_add_f32_dpp v141, v141, v141 quad_perm:[1,0,3,2] row_mask:0xf bank_mask:0xf bound_ctrl:1
	v_pk_mul_f32 v[116:117], v[86:87], v[52:53]
	v_add_f32_dpp v140, v140, v140 quad_perm:[2,3,0,1] row_mask:0xf bank_mask:0xf bound_ctrl:1
	v_add_f32_dpp v141, v141, v141 quad_perm:[2,3,0,1] row_mask:0xf bank_mask:0xf bound_ctrl:1
	v_pk_mul_f32 v[118:119], v[88:89], v[46:47]
	v_add_f32_dpp v140, v140, v140 row_half_mirror row_mask:0xf bank_mask:0xf bound_ctrl:1
	v_add_f32_dpp v141, v141, v141 row_half_mirror row_mask:0xf bank_mask:0xf bound_ctrl:1
	v_pk_mul_f32 v[120:121], v[90:91], v[48:49]
	ds_read_b128 v[26:29], v100 offset:38656
	ds_read_b128 v[30:33], v100 offset:38672
	v_mul_f32_e32 v142, v140, v98
	v_mul_f32_e32 v143, v99, v0
	ds_read_b32 v94, v101 offset:38912
	v_add_f32_e32 v141, v142, v141
	ds_read_b64 v[96:97], v1 offset:39168
	v_add_f32_e32 v141, v143, v141
	v_pk_fma_f32 v[114:115], v[140:141], v[62:63], v[114:115] op_sel_hi:[0,1,1]
	v_pk_fma_f32 v[116:117], v[140:141], v[64:65], v[116:117] op_sel_hi:[0,1,1]
	v_cvt_pk_bf16_f32 v142, v141, v141
	v_pk_fma_f32 v[84:85], v[0:1], v[54:55], v[114:115] op_sel_hi:[0,1,1]
	global_store_short v151, v142, s[100:101]
	v_pk_fma_f32 v[118:119], v[140:141], v[58:59], v[118:119] op_sel_hi:[0,1,1]
	v_pk_fma_f32 v[86:87], v[0:1], v[56:57], v[116:117] op_sel_hi:[0,1,1]
	v_pk_fma_f32 v[120:121], v[140:141], v[60:61], v[120:121] op_sel_hi:[0,1,1]
	v_pk_fma_f32 v[88:89], v[0:1], v[42:43], v[118:119] op_sel_hi:[0,1,1]
	v_pk_fma_f32 v[90:91], v[0:1], v[44:45], v[120:121] op_sel_hi:[0,1,1]
	s_waitcnt lgkmcnt(0)
	v_pk_fma_f32 v[106:107], v[84:85], v[34:35], 0 op_sel_hi:[1,1,0]
	v_pk_fma_f32 v[108:109], v[84:85], v[22:23], 0 op_sel_hi:[1,1,0]
	ds_read_b128 v[70:73], v100 offset:39200
	ds_read_b128 v[66:69], v100 offset:39216
	v_pk_fma_f32 v[106:107], v[86:87], v[36:37], v[106:107]
	v_pk_fma_f32 v[108:109], v[86:87], v[24:25], v[108:109]
	ds_read_b128 v[50:53], v100 offset:39456
	ds_read_b128 v[46:49], v100 offset:39472
	v_pk_fma_f32 v[106:107], v[88:89], v[38:39], v[106:107]
	v_pk_fma_f32 v[108:109], v[88:89], v[18:19], v[108:109]
	ds_read_b128 v[54:57], v100 offset:39712
	ds_read_b128 v[42:45], v100 offset:39728
	v_pk_fma_f32 v[106:107], v[90:91], v[40:41], v[106:107]
	v_pk_fma_f32 v[108:109], v[90:91], v[20:21], v[108:109]
	ds_read_b128 v[78:81], v100 offset:39968
	ds_read_b128 v[74:77], v100 offset:39984
	v_add_f32_e32 v130, v106, v107
	v_add_f32_e32 v131, v108, v109
	v_pk_mul_f32 v[114:115], v[84:85], v[2:3]
	v_add_f32_dpp v130, v130, v130 quad_perm:[1,0,3,2] row_mask:0xf bank_mask:0xf bound_ctrl:1
	v_add_f32_dpp v131, v131, v131 quad_perm:[1,0,3,2] row_mask:0xf bank_mask:0xf bound_ctrl:1
	v_pk_mul_f32 v[116:117], v[86:87], v[4:5]
	v_add_f32_dpp v130, v130, v130 quad_perm:[2,3,0,1] row_mask:0xf bank_mask:0xf bound_ctrl:1
	v_add_f32_dpp v131, v131, v131 quad_perm:[2,3,0,1] row_mask:0xf bank_mask:0xf bound_ctrl:1
	v_pk_mul_f32 v[118:119], v[88:89], v[6:7]
	v_add_f32_dpp v130, v130, v130 row_half_mirror row_mask:0xf bank_mask:0xf bound_ctrl:1
	v_add_f32_dpp v131, v131, v131 row_half_mirror row_mask:0xf bank_mask:0xf bound_ctrl:1
	v_pk_mul_f32 v[120:121], v[90:91], v[8:9]
	ds_read_b128 v[62:65], v100 offset:40224
	ds_read_b128 v[58:61], v100 offset:40240
	v_mul_f32_e32 v132, v130, v96
	v_mul_f32_e32 v133, v97, v94
	ds_read_b32 v0, v101 offset:40480
	v_add_f32_e32 v131, v132, v131
	ds_read_b64 v[98:99], v1 offset:40736
	v_add_f32_e32 v131, v133, v131
	v_pk_fma_f32 v[114:115], v[130:131], v[26:27], v[114:115] op_sel_hi:[0,1,1]
	v_pk_fma_f32 v[116:117], v[130:131], v[28:29], v[116:117] op_sel_hi:[0,1,1]
	v_cvt_pk_bf16_f32 v132, v131, v131
	v_pk_fma_f32 v[84:85], v[94:95], v[10:11], v[114:115] op_sel_hi:[0,1,1]
	global_store_short v152, v132, s[100:101]
	v_pk_fma_f32 v[118:119], v[130:131], v[30:31], v[118:119] op_sel_hi:[0,1,1]
	v_pk_fma_f32 v[86:87], v[94:95], v[12:13], v[116:117] op_sel_hi:[0,1,1]
	v_pk_fma_f32 v[120:121], v[130:131], v[32:33], v[120:121] op_sel_hi:[0,1,1]
	v_pk_fma_f32 v[88:89], v[94:95], v[14:15], v[118:119] op_sel_hi:[0,1,1]
	v_pk_fma_f32 v[90:91], v[94:95], v[16:17], v[120:121] op_sel_hi:[0,1,1]
	s_waitcnt lgkmcnt(0)
	v_pk_fma_f32 v[110:111], v[84:85], v[78:79], 0 op_sel_hi:[1,1,0]
	v_pk_fma_f32 v[112:113], v[84:85], v[70:71], 0 op_sel_hi:[1,1,0]
	ds_read_b128 v[22:25], v100 offset:40768
	ds_read_b128 v[18:21], v100 offset:40784
	v_pk_fma_f32 v[110:111], v[86:87], v[80:81], v[110:111]
	v_pk_fma_f32 v[112:113], v[86:87], v[72:73], v[112:113]
	ds_read_b128 v[2:5], v100 offset:41024
	ds_read_b128 v[6:9], v100 offset:41040
	v_pk_fma_f32 v[110:111], v[88:89], v[74:75], v[110:111]
	v_pk_fma_f32 v[112:113], v[88:89], v[66:67], v[112:113]
	ds_read_b128 v[10:13], v100 offset:41280
	ds_read_b128 v[14:17], v100 offset:41296
	v_pk_fma_f32 v[110:111], v[90:91], v[76:77], v[110:111]
	v_pk_fma_f32 v[112:113], v[90:91], v[68:69], v[112:113]
	ds_read_b128 v[34:37], v100 offset:41536
	ds_read_b128 v[38:41], v100 offset:41552
	v_add_f32_e32 v140, v110, v111
	v_add_f32_e32 v141, v112, v113
	v_pk_mul_f32 v[114:115], v[84:85], v[50:51]
	v_add_f32_dpp v140, v140, v140 quad_perm:[1,0,3,2] row_mask:0xf bank_mask:0xf bound_ctrl:1
	v_add_f32_dpp v141, v141, v141 quad_perm:[1,0,3,2] row_mask:0xf bank_mask:0xf bound_ctrl:1
	v_pk_mul_f32 v[116:117], v[86:87], v[52:53]
	v_add_f32_dpp v140, v140, v140 quad_perm:[2,3,0,1] row_mask:0xf bank_mask:0xf bound_ctrl:1
	v_add_f32_dpp v141, v141, v141 quad_perm:[2,3,0,1] row_mask:0xf bank_mask:0xf bound_ctrl:1
	v_pk_mul_f32 v[118:119], v[88:89], v[46:47]
	v_add_f32_dpp v140, v140, v140 row_half_mirror row_mask:0xf bank_mask:0xf bound_ctrl:1
	v_add_f32_dpp v141, v141, v141 row_half_mirror row_mask:0xf bank_mask:0xf bound_ctrl:1
	v_pk_mul_f32 v[120:121], v[90:91], v[48:49]
	ds_read_b128 v[26:29], v100 offset:41792
	ds_read_b128 v[30:33], v100 offset:41808
	v_mul_f32_e32 v142, v140, v98
	v_mul_f32_e32 v143, v99, v0
	ds_read_b32 v94, v101 offset:42048
	v_add_f32_e32 v141, v142, v141
	ds_read_b64 v[96:97], v1 offset:42304
	v_add_f32_e32 v141, v143, v141
	v_pk_fma_f32 v[114:115], v[140:141], v[62:63], v[114:115] op_sel_hi:[0,1,1]
	v_pk_fma_f32 v[116:117], v[140:141], v[64:65], v[116:117] op_sel_hi:[0,1,1]
	v_cvt_pk_bf16_f32 v142, v141, v141
	v_pk_fma_f32 v[84:85], v[0:1], v[54:55], v[114:115] op_sel_hi:[0,1,1]
	global_store_short v153, v142, s[100:101]
	v_pk_fma_f32 v[118:119], v[140:141], v[58:59], v[118:119] op_sel_hi:[0,1,1]
	v_pk_fma_f32 v[86:87], v[0:1], v[56:57], v[116:117] op_sel_hi:[0,1,1]
	v_pk_fma_f32 v[120:121], v[140:141], v[60:61], v[120:121] op_sel_hi:[0,1,1]
	v_pk_fma_f32 v[88:89], v[0:1], v[42:43], v[118:119] op_sel_hi:[0,1,1]
	v_pk_fma_f32 v[90:91], v[0:1], v[44:45], v[120:121] op_sel_hi:[0,1,1]
	s_waitcnt lgkmcnt(0)
	v_pk_fma_f32 v[106:107], v[84:85], v[34:35], 0 op_sel_hi:[1,1,0]
	v_pk_fma_f32 v[108:109], v[84:85], v[22:23], 0 op_sel_hi:[1,1,0]
	ds_read_b128 v[70:73], v100 offset:42336
	ds_read_b128 v[66:69], v100 offset:42352
	v_pk_fma_f32 v[106:107], v[86:87], v[36:37], v[106:107]
	v_pk_fma_f32 v[108:109], v[86:87], v[24:25], v[108:109]
	ds_read_b128 v[50:53], v100 offset:42592
	ds_read_b128 v[46:49], v100 offset:42608
	v_pk_fma_f32 v[106:107], v[88:89], v[38:39], v[106:107]
	v_pk_fma_f32 v[108:109], v[88:89], v[18:19], v[108:109]
	ds_read_b128 v[54:57], v100 offset:42848
	ds_read_b128 v[42:45], v100 offset:42864
	v_pk_fma_f32 v[106:107], v[90:91], v[40:41], v[106:107]
	v_pk_fma_f32 v[108:109], v[90:91], v[20:21], v[108:109]
	ds_read_b128 v[78:81], v100 offset:43104
	ds_read_b128 v[74:77], v100 offset:43120
	v_add_f32_e32 v130, v106, v107
	v_add_f32_e32 v131, v108, v109
	v_pk_mul_f32 v[114:115], v[84:85], v[2:3]
	v_add_f32_dpp v130, v130, v130 quad_perm:[1,0,3,2] row_mask:0xf bank_mask:0xf bound_ctrl:1
	v_add_f32_dpp v131, v131, v131 quad_perm:[1,0,3,2] row_mask:0xf bank_mask:0xf bound_ctrl:1
	v_pk_mul_f32 v[116:117], v[86:87], v[4:5]
	v_add_f32_dpp v130, v130, v130 quad_perm:[2,3,0,1] row_mask:0xf bank_mask:0xf bound_ctrl:1
	v_add_f32_dpp v131, v131, v131 quad_perm:[2,3,0,1] row_mask:0xf bank_mask:0xf bound_ctrl:1
	v_pk_mul_f32 v[118:119], v[88:89], v[6:7]
	v_add_f32_dpp v130, v130, v130 row_half_mirror row_mask:0xf bank_mask:0xf bound_ctrl:1
	v_add_f32_dpp v131, v131, v131 row_half_mirror row_mask:0xf bank_mask:0xf bound_ctrl:1
	v_pk_mul_f32 v[120:121], v[90:91], v[8:9]
	ds_read_b128 v[62:65], v100 offset:43360
	ds_read_b128 v[58:61], v100 offset:43376
	v_mul_f32_e32 v132, v130, v96
	v_mul_f32_e32 v133, v97, v94
	ds_read_b32 v0, v101 offset:43616
	v_add_f32_e32 v131, v132, v131
	ds_read_b64 v[98:99], v1 offset:43872
	v_add_f32_e32 v131, v133, v131
	v_pk_fma_f32 v[114:115], v[130:131], v[26:27], v[114:115] op_sel_hi:[0,1,1]
	v_pk_fma_f32 v[116:117], v[130:131], v[28:29], v[116:117] op_sel_hi:[0,1,1]
	v_cvt_pk_bf16_f32 v132, v131, v131
	v_pk_fma_f32 v[84:85], v[94:95], v[10:11], v[114:115] op_sel_hi:[0,1,1]
	global_store_short v154, v132, s[100:101]
	v_pk_fma_f32 v[118:119], v[130:131], v[30:31], v[118:119] op_sel_hi:[0,1,1]
	v_pk_fma_f32 v[86:87], v[94:95], v[12:13], v[116:117] op_sel_hi:[0,1,1]
	v_pk_fma_f32 v[120:121], v[130:131], v[32:33], v[120:121] op_sel_hi:[0,1,1]
	v_pk_fma_f32 v[88:89], v[94:95], v[14:15], v[118:119] op_sel_hi:[0,1,1]
	v_pk_fma_f32 v[90:91], v[94:95], v[16:17], v[120:121] op_sel_hi:[0,1,1]
	s_waitcnt lgkmcnt(0)
	v_pk_fma_f32 v[110:111], v[84:85], v[78:79], 0 op_sel_hi:[1,1,0]
	v_pk_fma_f32 v[112:113], v[84:85], v[70:71], 0 op_sel_hi:[1,1,0]
	ds_read_b128 v[22:25], v100 offset:43904
	ds_read_b128 v[18:21], v100 offset:43920
	v_pk_fma_f32 v[110:111], v[86:87], v[80:81], v[110:111]
	v_pk_fma_f32 v[112:113], v[86:87], v[72:73], v[112:113]
	ds_read_b128 v[2:5], v100 offset:44160
	ds_read_b128 v[6:9], v100 offset:44176
	v_pk_fma_f32 v[110:111], v[88:89], v[74:75], v[110:111]
	v_pk_fma_f32 v[112:113], v[88:89], v[66:67], v[112:113]
	ds_read_b128 v[10:13], v100 offset:44416
	ds_read_b128 v[14:17], v100 offset:44432
	v_pk_fma_f32 v[110:111], v[90:91], v[76:77], v[110:111]
	v_pk_fma_f32 v[112:113], v[90:91], v[68:69], v[112:113]
	ds_read_b128 v[34:37], v100 offset:44672
	ds_read_b128 v[38:41], v100 offset:44688
	v_add_f32_e32 v140, v110, v111
	v_add_f32_e32 v141, v112, v113
	v_pk_mul_f32 v[114:115], v[84:85], v[50:51]
	v_add_f32_dpp v140, v140, v140 quad_perm:[1,0,3,2] row_mask:0xf bank_mask:0xf bound_ctrl:1
	v_add_f32_dpp v141, v141, v141 quad_perm:[1,0,3,2] row_mask:0xf bank_mask:0xf bound_ctrl:1
	v_pk_mul_f32 v[116:117], v[86:87], v[52:53]
	v_add_f32_dpp v140, v140, v140 quad_perm:[2,3,0,1] row_mask:0xf bank_mask:0xf bound_ctrl:1
	v_add_f32_dpp v141, v141, v141 quad_perm:[2,3,0,1] row_mask:0xf bank_mask:0xf bound_ctrl:1
	v_pk_mul_f32 v[118:119], v[88:89], v[46:47]
	v_add_f32_dpp v140, v140, v140 row_half_mirror row_mask:0xf bank_mask:0xf bound_ctrl:1
	v_add_f32_dpp v141, v141, v141 row_half_mirror row_mask:0xf bank_mask:0xf bound_ctrl:1
	v_pk_mul_f32 v[120:121], v[90:91], v[48:49]
	ds_read_b128 v[26:29], v100 offset:44928
	ds_read_b128 v[30:33], v100 offset:44944
	v_mul_f32_e32 v142, v140, v98
	v_mul_f32_e32 v143, v99, v0
	ds_read_b32 v94, v101 offset:45184
	v_add_f32_e32 v141, v142, v141
	ds_read_b64 v[96:97], v1 offset:45440
	v_add_f32_e32 v141, v143, v141
	v_pk_fma_f32 v[114:115], v[140:141], v[62:63], v[114:115] op_sel_hi:[0,1,1]
	v_pk_fma_f32 v[116:117], v[140:141], v[64:65], v[116:117] op_sel_hi:[0,1,1]
	v_cvt_pk_bf16_f32 v142, v141, v141
	v_pk_fma_f32 v[84:85], v[0:1], v[54:55], v[114:115] op_sel_hi:[0,1,1]
	global_store_short v155, v142, s[100:101]
	v_pk_fma_f32 v[118:119], v[140:141], v[58:59], v[118:119] op_sel_hi:[0,1,1]
	v_pk_fma_f32 v[86:87], v[0:1], v[56:57], v[116:117] op_sel_hi:[0,1,1]
	v_pk_fma_f32 v[120:121], v[140:141], v[60:61], v[120:121] op_sel_hi:[0,1,1]
	v_pk_fma_f32 v[88:89], v[0:1], v[42:43], v[118:119] op_sel_hi:[0,1,1]
	v_pk_fma_f32 v[90:91], v[0:1], v[44:45], v[120:121] op_sel_hi:[0,1,1]
	s_waitcnt lgkmcnt(0)
	v_pk_fma_f32 v[106:107], v[84:85], v[34:35], 0 op_sel_hi:[1,1,0]
	v_pk_fma_f32 v[108:109], v[84:85], v[22:23], 0 op_sel_hi:[1,1,0]
	ds_read_b128 v[70:73], v100 offset:45472
	ds_read_b128 v[66:69], v100 offset:45488
	v_pk_fma_f32 v[106:107], v[86:87], v[36:37], v[106:107]
	v_pk_fma_f32 v[108:109], v[86:87], v[24:25], v[108:109]
	ds_read_b128 v[50:53], v100 offset:45728
	ds_read_b128 v[46:49], v100 offset:45744
	v_pk_fma_f32 v[106:107], v[88:89], v[38:39], v[106:107]
	v_pk_fma_f32 v[108:109], v[88:89], v[18:19], v[108:109]
	ds_read_b128 v[54:57], v100 offset:45984
	ds_read_b128 v[42:45], v100 offset:46000
	v_pk_fma_f32 v[106:107], v[90:91], v[40:41], v[106:107]
	v_pk_fma_f32 v[108:109], v[90:91], v[20:21], v[108:109]
	ds_read_b128 v[78:81], v100 offset:46240
	ds_read_b128 v[74:77], v100 offset:46256
	v_add_f32_e32 v130, v106, v107
	v_add_f32_e32 v131, v108, v109
	v_pk_mul_f32 v[114:115], v[84:85], v[2:3]
	v_add_f32_dpp v130, v130, v130 quad_perm:[1,0,3,2] row_mask:0xf bank_mask:0xf bound_ctrl:1
	v_add_f32_dpp v131, v131, v131 quad_perm:[1,0,3,2] row_mask:0xf bank_mask:0xf bound_ctrl:1
	v_pk_mul_f32 v[116:117], v[86:87], v[4:5]
	v_add_f32_dpp v130, v130, v130 quad_perm:[2,3,0,1] row_mask:0xf bank_mask:0xf bound_ctrl:1
	v_add_f32_dpp v131, v131, v131 quad_perm:[2,3,0,1] row_mask:0xf bank_mask:0xf bound_ctrl:1
	v_pk_mul_f32 v[118:119], v[88:89], v[6:7]
	v_add_f32_dpp v130, v130, v130 row_half_mirror row_mask:0xf bank_mask:0xf bound_ctrl:1
	v_add_f32_dpp v131, v131, v131 row_half_mirror row_mask:0xf bank_mask:0xf bound_ctrl:1
	v_pk_mul_f32 v[120:121], v[90:91], v[8:9]
	ds_read_b128 v[62:65], v100 offset:46496
	ds_read_b128 v[58:61], v100 offset:46512
	v_mul_f32_e32 v132, v130, v96
	v_mul_f32_e32 v133, v97, v94
	ds_read_b32 v0, v101 offset:46752
	v_add_f32_e32 v131, v132, v131
	ds_read_b64 v[98:99], v1 offset:47008
	v_add_f32_e32 v131, v133, v131
	v_pk_fma_f32 v[114:115], v[130:131], v[26:27], v[114:115] op_sel_hi:[0,1,1]
	v_pk_fma_f32 v[116:117], v[130:131], v[28:29], v[116:117] op_sel_hi:[0,1,1]
	v_cvt_pk_bf16_f32 v132, v131, v131
	v_pk_fma_f32 v[84:85], v[94:95], v[10:11], v[114:115] op_sel_hi:[0,1,1]
	global_store_short v156, v132, s[100:101]
	v_pk_fma_f32 v[118:119], v[130:131], v[30:31], v[118:119] op_sel_hi:[0,1,1]
	v_pk_fma_f32 v[86:87], v[94:95], v[12:13], v[116:117] op_sel_hi:[0,1,1]
	v_pk_fma_f32 v[120:121], v[130:131], v[32:33], v[120:121] op_sel_hi:[0,1,1]
	v_pk_fma_f32 v[88:89], v[94:95], v[14:15], v[118:119] op_sel_hi:[0,1,1]
	v_pk_fma_f32 v[90:91], v[94:95], v[16:17], v[120:121] op_sel_hi:[0,1,1]
	s_waitcnt lgkmcnt(0)
	v_pk_fma_f32 v[110:111], v[84:85], v[78:79], 0 op_sel_hi:[1,1,0]
	v_pk_fma_f32 v[112:113], v[84:85], v[70:71], 0 op_sel_hi:[1,1,0]
	ds_read_b128 v[22:25], v100 offset:47040
	ds_read_b128 v[18:21], v100 offset:47056
	v_pk_fma_f32 v[110:111], v[86:87], v[80:81], v[110:111]
	v_pk_fma_f32 v[112:113], v[86:87], v[72:73], v[112:113]
	ds_read_b128 v[2:5], v100 offset:47296
	ds_read_b128 v[6:9], v100 offset:47312
	v_pk_fma_f32 v[110:111], v[88:89], v[74:75], v[110:111]
	v_pk_fma_f32 v[112:113], v[88:89], v[66:67], v[112:113]
	ds_read_b128 v[10:13], v100 offset:47552
	ds_read_b128 v[14:17], v100 offset:47568
	v_pk_fma_f32 v[110:111], v[90:91], v[76:77], v[110:111]
	v_pk_fma_f32 v[112:113], v[90:91], v[68:69], v[112:113]
	ds_read_b128 v[34:37], v100 offset:47808
	ds_read_b128 v[38:41], v100 offset:47824
	v_add_f32_e32 v140, v110, v111
	v_add_f32_e32 v141, v112, v113
	v_pk_mul_f32 v[114:115], v[84:85], v[50:51]
	v_add_f32_dpp v140, v140, v140 quad_perm:[1,0,3,2] row_mask:0xf bank_mask:0xf bound_ctrl:1
	v_add_f32_dpp v141, v141, v141 quad_perm:[1,0,3,2] row_mask:0xf bank_mask:0xf bound_ctrl:1
	v_pk_mul_f32 v[116:117], v[86:87], v[52:53]
	v_add_f32_dpp v140, v140, v140 quad_perm:[2,3,0,1] row_mask:0xf bank_mask:0xf bound_ctrl:1
	v_add_f32_dpp v141, v141, v141 quad_perm:[2,3,0,1] row_mask:0xf bank_mask:0xf bound_ctrl:1
	v_pk_mul_f32 v[118:119], v[88:89], v[46:47]
	v_add_f32_dpp v140, v140, v140 row_half_mirror row_mask:0xf bank_mask:0xf bound_ctrl:1
	v_add_f32_dpp v141, v141, v141 row_half_mirror row_mask:0xf bank_mask:0xf bound_ctrl:1
	v_pk_mul_f32 v[120:121], v[90:91], v[48:49]
	ds_read_b128 v[26:29], v100 offset:48064
	ds_read_b128 v[30:33], v100 offset:48080
	v_mul_f32_e32 v142, v140, v98
	v_mul_f32_e32 v143, v99, v0
	ds_read_b32 v94, v101 offset:48320
	v_add_f32_e32 v141, v142, v141
	ds_read_b64 v[96:97], v1 offset:48576
	v_add_f32_e32 v141, v143, v141
	v_pk_fma_f32 v[114:115], v[140:141], v[62:63], v[114:115] op_sel_hi:[0,1,1]
	v_pk_fma_f32 v[116:117], v[140:141], v[64:65], v[116:117] op_sel_hi:[0,1,1]
	v_cvt_pk_bf16_f32 v142, v141, v141
	v_pk_fma_f32 v[84:85], v[0:1], v[54:55], v[114:115] op_sel_hi:[0,1,1]
	global_store_short v157, v142, s[100:101]
	v_pk_fma_f32 v[118:119], v[140:141], v[58:59], v[118:119] op_sel_hi:[0,1,1]
	v_pk_fma_f32 v[86:87], v[0:1], v[56:57], v[116:117] op_sel_hi:[0,1,1]
	v_pk_fma_f32 v[120:121], v[140:141], v[60:61], v[120:121] op_sel_hi:[0,1,1]
	v_pk_fma_f32 v[88:89], v[0:1], v[42:43], v[118:119] op_sel_hi:[0,1,1]
	v_pk_fma_f32 v[90:91], v[0:1], v[44:45], v[120:121] op_sel_hi:[0,1,1]
	s_waitcnt lgkmcnt(0)
	v_pk_fma_f32 v[106:107], v[84:85], v[34:35], 0 op_sel_hi:[1,1,0]
	v_pk_fma_f32 v[108:109], v[84:85], v[22:23], 0 op_sel_hi:[1,1,0]
	ds_read_b128 v[70:73], v100 offset:48608
	ds_read_b128 v[66:69], v100 offset:48624
	v_pk_fma_f32 v[106:107], v[86:87], v[36:37], v[106:107]
	v_pk_fma_f32 v[108:109], v[86:87], v[24:25], v[108:109]
	ds_read_b128 v[50:53], v100 offset:48864
	ds_read_b128 v[46:49], v100 offset:48880
	v_pk_fma_f32 v[106:107], v[88:89], v[38:39], v[106:107]
	v_pk_fma_f32 v[108:109], v[88:89], v[18:19], v[108:109]
	ds_read_b128 v[54:57], v100 offset:49120
	ds_read_b128 v[42:45], v100 offset:49136
	v_pk_fma_f32 v[106:107], v[90:91], v[40:41], v[106:107]
	v_pk_fma_f32 v[108:109], v[90:91], v[20:21], v[108:109]
	ds_read_b128 v[78:81], v100 offset:49376
	ds_read_b128 v[74:77], v100 offset:49392
	v_add_f32_e32 v130, v106, v107
	v_add_f32_e32 v131, v108, v109
	v_pk_mul_f32 v[114:115], v[84:85], v[2:3]
	v_add_f32_dpp v130, v130, v130 quad_perm:[1,0,3,2] row_mask:0xf bank_mask:0xf bound_ctrl:1
	v_add_f32_dpp v131, v131, v131 quad_perm:[1,0,3,2] row_mask:0xf bank_mask:0xf bound_ctrl:1
	v_pk_mul_f32 v[116:117], v[86:87], v[4:5]
	v_add_f32_dpp v130, v130, v130 quad_perm:[2,3,0,1] row_mask:0xf bank_mask:0xf bound_ctrl:1
	v_add_f32_dpp v131, v131, v131 quad_perm:[2,3,0,1] row_mask:0xf bank_mask:0xf bound_ctrl:1
	v_pk_mul_f32 v[118:119], v[88:89], v[6:7]
	v_add_f32_dpp v130, v130, v130 row_half_mirror row_mask:0xf bank_mask:0xf bound_ctrl:1
	v_add_f32_dpp v131, v131, v131 row_half_mirror row_mask:0xf bank_mask:0xf bound_ctrl:1
	v_pk_mul_f32 v[120:121], v[90:91], v[8:9]
	ds_read_b128 v[62:65], v100 offset:49632
	ds_read_b128 v[58:61], v100 offset:49648
	v_mul_f32_e32 v132, v130, v96
	v_mul_f32_e32 v133, v97, v94
	ds_read_b32 v0, v101 offset:49888
	v_add_f32_e32 v131, v132, v131
	ds_read_b64 v[98:99], v1 offset:50144
	v_add_f32_e32 v131, v133, v131
	v_pk_fma_f32 v[114:115], v[130:131], v[26:27], v[114:115] op_sel_hi:[0,1,1]
	v_pk_fma_f32 v[116:117], v[130:131], v[28:29], v[116:117] op_sel_hi:[0,1,1]
	v_cvt_pk_bf16_f32 v132, v131, v131
	v_pk_fma_f32 v[84:85], v[94:95], v[10:11], v[114:115] op_sel_hi:[0,1,1]
	global_store_short v158, v132, s[100:101]
	v_pk_fma_f32 v[118:119], v[130:131], v[30:31], v[118:119] op_sel_hi:[0,1,1]
	v_pk_fma_f32 v[86:87], v[94:95], v[12:13], v[116:117] op_sel_hi:[0,1,1]
	v_pk_fma_f32 v[120:121], v[130:131], v[32:33], v[120:121] op_sel_hi:[0,1,1]
	v_pk_fma_f32 v[88:89], v[94:95], v[14:15], v[118:119] op_sel_hi:[0,1,1]
	v_pk_fma_f32 v[90:91], v[94:95], v[16:17], v[120:121] op_sel_hi:[0,1,1]
	s_waitcnt lgkmcnt(0)
	v_pk_fma_f32 v[110:111], v[84:85], v[78:79], 0 op_sel_hi:[1,1,0]
	v_pk_fma_f32 v[112:113], v[84:85], v[70:71], 0 op_sel_hi:[1,1,0]
	v_pk_fma_f32 v[110:111], v[86:87], v[80:81], v[110:111]
	v_pk_fma_f32 v[112:113], v[86:87], v[72:73], v[112:113]
	v_pk_fma_f32 v[110:111], v[88:89], v[74:75], v[110:111]
	v_pk_fma_f32 v[112:113], v[88:89], v[66:67], v[112:113]
	v_pk_fma_f32 v[110:111], v[90:91], v[76:77], v[110:111]
	v_pk_fma_f32 v[112:113], v[90:91], v[68:69], v[112:113]
	v_add_f32_e32 v140, v110, v111
	v_add_f32_e32 v141, v112, v113
	v_pk_mul_f32 v[114:115], v[84:85], v[50:51]
	v_add_f32_dpp v140, v140, v140 quad_perm:[1,0,3,2] row_mask:0xf bank_mask:0xf bound_ctrl:1
	v_add_f32_dpp v141, v141, v141 quad_perm:[1,0,3,2] row_mask:0xf bank_mask:0xf bound_ctrl:1
	v_pk_mul_f32 v[116:117], v[86:87], v[52:53]
	v_add_f32_dpp v140, v140, v140 quad_perm:[2,3,0,1] row_mask:0xf bank_mask:0xf bound_ctrl:1
	v_add_f32_dpp v141, v141, v141 quad_perm:[2,3,0,1] row_mask:0xf bank_mask:0xf bound_ctrl:1
	v_pk_mul_f32 v[118:119], v[88:89], v[46:47]
	v_add_f32_dpp v140, v140, v140 row_half_mirror row_mask:0xf bank_mask:0xf bound_ctrl:1
	v_add_f32_dpp v141, v141, v141 row_half_mirror row_mask:0xf bank_mask:0xf bound_ctrl:1
	v_pk_mul_f32 v[120:121], v[90:91], v[48:49]
	v_mul_f32_e32 v142, v140, v98
	v_mul_f32_e32 v143, v99, v0
	v_add_f32_e32 v141, v142, v141
	v_add_f32_e32 v141, v143, v141
	v_pk_fma_f32 v[114:115], v[140:141], v[62:63], v[114:115] op_sel_hi:[0,1,1]
	v_pk_fma_f32 v[116:117], v[140:141], v[64:65], v[116:117] op_sel_hi:[0,1,1]
	v_cvt_pk_bf16_f32 v142, v141, v141
	v_pk_fma_f32 v[84:85], v[0:1], v[54:55], v[114:115] op_sel_hi:[0,1,1]
	global_store_short v159, v142, s[100:101]
	v_pk_fma_f32 v[118:119], v[140:141], v[58:59], v[118:119] op_sel_hi:[0,1,1]
	v_pk_fma_f32 v[86:87], v[0:1], v[56:57], v[116:117] op_sel_hi:[0,1,1]
	v_pk_fma_f32 v[120:121], v[140:141], v[60:61], v[120:121] op_sel_hi:[0,1,1]
	v_pk_fma_f32 v[88:89], v[0:1], v[42:43], v[118:119] op_sel_hi:[0,1,1]
	v_pk_fma_f32 v[90:91], v[0:1], v[44:45], v[120:121] op_sel_hi:[0,1,1]
	s_branch .LBB0_852
